# P3 epilogue hand-rewritten: gate loads 4 row groups ahead, no junk stores for branches 0/1, branch 2 loads only its own gate
# speedup vs baseline: 1.0123x; 1.0123x over previous
; __device__ __forceinline__ float frcp(float x) { return __builtin_amdgcn_rcpf(x); }
; __device__ __forceinline__ u32x4 pack8(f32x4 a, f32x4 b) { u32x4 w; w.x = pk_bf16(a[0], a[1]); w.y = pk_bf16(a[2], a[3]); w.z = pk_bf16(b[0], b[1]); w.w = pk_bf16(b[2], b[3]); return w; }
; __device__ __forceinline__ void unpack8(u32x4 w, float* f) { f[0] = bf_lo(w.x); f[1] = bf_hi(w.x); f[2] = bf_lo(w.y); f[3] = bf_hi(w.y); f[4] = bf_lo(w.z); f[5] = bf_hi(w.z); f[6] = bf_lo(w.w); f[7] = bf_hi(w.w); }
; #define E2_LOAD(buf, g) do { const bf16_t* gp_ = G + (size_t)(rowb + ((g) >> 2) * 128 + ((g) & 3) * 16) * GATEW + br * 1024 + colb; \
;         L[buf][0] = *(const u32x4*)gp_; L[buf][1] = *(const u32x4*)(gp_ + 1024); L[buf][2] = *(const u32x4*)(gp_ + 128); L[buf][3] = *(const u32x4*)(gp_ + 128 + 1024); } while (0)
;     __device__ __forceinline__ bool operator()(f32x4 (&acc)[2][2][4][2], const pg8::Unit& u, int wr, int wc, int fr, int fq) const {
;         const int rowb = u.pm * 256 + wr * 64 + fr, colb = u.pn * 256 + wc * 32 + 8 * fq;
;         const int br = u.kind; const bool last = br == 2;
;         u32x4 L[2][4];
;     ...
;         E2_LOAD(0, 0);
; #pragma unroll
;         for (int g = 0; g < 8; ++g) {
;             if (g < 7) E2_LOAD((g + 1) & 1, g + 1);
;             const int ai = g >> 2, m = g & 3, row = rowb + ai * 128 + m * 16;
; #pragma unroll
;             for (int bj = 0; bj < 2; ++bj) { const int col = colb + bj * 128; f32x4& v0 = acc[ai][bj][m][0]; f32x4& v1 = acc[ai][bj][m][1];
;                 float c[8], n[8]; unpack8(L[g & 1][2 * bj], c); unpack8(L[g & 1][2 * bj + 1], n); f32x4 o0, o1;
; #pragma unroll
;                 for (int j = 0; j < 8; ++j) { c[j] = fmaxf(c[j], 1e-30f); n[j] = last ? 1.0f : fmaxf(n[j], 1e-30f); }
; #pragma unroll
;                 for (int j = 0; j < 4; ++j) { v0[j] *= c[j] * frcp(n[j]); v1[j] *= c[4 + j] * frcp(n[4 + j]); }
; #pragma unroll
;                 for (int j = 0; j < 4; ++j) { o0[j] = v0[j] * n[j]; o1[j] = v1[j] * n[4 + j]; }
;                 *(u32x4*)(last ? MG + (size_t)row * DM + col : junk + (threadIdx.x & 511) * 8) = pack8(o0, o1); }
.LBB0_762:
	v_lshl_add_u32 v182, s6, 8, v190
	v_mov_b64_e32 v[184:185], s[12:13]
	s_cmp_eq_u32 s70, 2
	v_mad_i64_i32 v[132:133], s[54:55], v182, s65, v[184:185]
	s_cselect_b64 s[6:7], -1, 0
	s_lshl_b32 s54, s70, 10
	v_lshl_or_b32 v130, s69, 8, v192
	s_ashr_i32 s55, s54, 31
	s_lshl_b64 s[54:55], s[54:55], 1
	v_ashrrev_i32_e32 v131, 31, v130
	v_lshl_add_u64 v[132:133], v[132:133], 0, s[54:55]
	v_lshlrev_b64 v[180:181], 1, v[130:131]
	v_lshl_add_u64 v[130:131], v[132:133], 0, v[180:181]
	s_mov_b32 s58, 0x18000
	s_mov_b32 s59, 0
	s_mov_b32 s54, 0x78000
	s_mov_b32 s55, 0
	s_mov_b32 s56, 0xffff0000
	s_mov_b32 s57, 0xda24260
	s_and_b64 vcc, exec, s[6:7]
	s_cbranch_vccnz .Le2_last
	global_load_dwordx4 v[134:137], v[130:131], off
	global_load_dwordx4 v[138:141], v[130:131], off offset:2048
	global_load_dwordx4 v[142:145], v[130:131], off offset:256
	global_load_dwordx4 v[146:149], v[130:131], off offset:2304
	v_lshl_add_u64 v[130:131], v[130:131], 0, s[58:59]
	global_load_dwordx4 v[150:153], v[130:131], off
	global_load_dwordx4 v[154:157], v[130:131], off offset:2048
	global_load_dwordx4 v[158:161], v[130:131], off offset:256
	global_load_dwordx4 v[162:165], v[130:131], off offset:2304
	v_lshl_add_u64 v[130:131], v[130:131], 0, s[58:59]
	global_load_dwordx4 v[220:223], v[130:131], off
	global_load_dwordx4 v[224:227], v[130:131], off offset:2048
	global_load_dwordx4 v[228:231], v[130:131], off offset:256
	global_load_dwordx4 v[232:235], v[130:131], off offset:2304
	v_lshl_add_u64 v[130:131], v[130:131], 0, s[58:59]
	global_load_dwordx4 v[242:245], v[130:131], off
	global_load_dwordx4 v[246:249], v[130:131], off offset:2048
	global_load_dwordx4 v[210:213], v[130:131], off offset:256
	global_load_dwordx4 v[214:217], v[130:131], off offset:2304
	v_lshl_add_u64 v[130:131], v[130:131], 0, s[54:55]
	s_waitcnt vmcnt(12)
	v_lshlrev_b32_e32 v184, 16, v134
	v_and_b32_e32 v185, s56, v134
	v_lshlrev_b32_e32 v186, 16, v135
	v_and_b32_e32 v187, s56, v135
	v_lshlrev_b32_e32 v188, 16, v136
	v_and_b32_e32 v189, s56, v136
	v_lshlrev_b32_e32 v218, 16, v137
	v_and_b32_e32 v219, s56, v137
	v_max_f32_e32 v184, s57, v184
	v_max_f32_e32 v185, s57, v185
	v_max_f32_e32 v186, s57, v186
	v_max_f32_e32 v187, s57, v187
	v_max_f32_e32 v188, s57, v188
	v_max_f32_e32 v189, s57, v189
	v_max_f32_e32 v218, s57, v218
	v_max_f32_e32 v219, s57, v219
	v_lshlrev_b32_e32 v134, 16, v138
	v_and_b32_e32 v138, s56, v138
	v_lshlrev_b32_e32 v135, 16, v139
	v_and_b32_e32 v139, s56, v139
	v_lshlrev_b32_e32 v136, 16, v140
	v_and_b32_e32 v140, s56, v140
	v_lshlrev_b32_e32 v137, 16, v141
	v_and_b32_e32 v141, s56, v141
	v_max_f32_e32 v134, s57, v134
	v_max_f32_e32 v138, s57, v138
	v_max_f32_e32 v135, s57, v135
	v_max_f32_e32 v139, s57, v139
	v_max_f32_e32 v136, s57, v136
	v_max_f32_e32 v140, s57, v140
	v_max_f32_e32 v137, s57, v137
	v_max_f32_e32 v141, s57, v141
	v_rcp_f32_e32 v134, v134
	v_rcp_f32_e32 v138, v138
	v_rcp_f32_e32 v135, v135
	v_rcp_f32_e32 v139, v139
	v_rcp_f32_e32 v136, v136
	v_rcp_f32_e32 v140, v140
	v_rcp_f32_e32 v137, v137
	v_rcp_f32_e32 v141, v141
	v_mul_f32_e32 v184, v184, v134
	v_mul_f32_e32 v185, v185, v138
	v_mul_f32_e32 v186, v186, v135
	v_mul_f32_e32 v187, v187, v139
	v_mul_f32_e32 v188, v188, v136
	v_mul_f32_e32 v189, v189, v140
	v_mul_f32_e32 v218, v218, v137
	v_mul_f32_e32 v219, v219, v141
	v_pk_mul_f32 v[126:127], v[126:127], v[184:185]
	v_pk_mul_f32 v[128:129], v[128:129], v[186:187]
	v_pk_mul_f32 v[122:123], v[122:123], v[188:189]
	v_pk_mul_f32 v[124:125], v[124:125], v[218:219]
	v_lshlrev_b32_e32 v184, 16, v142
	v_and_b32_e32 v185, s56, v142
	v_lshlrev_b32_e32 v186, 16, v143
	v_and_b32_e32 v187, s56, v143
	v_lshlrev_b32_e32 v188, 16, v144
	v_and_b32_e32 v189, s56, v144
	v_lshlrev_b32_e32 v218, 16, v145
	v_and_b32_e32 v219, s56, v145
	v_max_f32_e32 v184, s57, v184
	v_max_f32_e32 v185, s57, v185
	v_max_f32_e32 v186, s57, v186
	v_max_f32_e32 v187, s57, v187
	v_max_f32_e32 v188, s57, v188
	v_max_f32_e32 v189, s57, v189
	v_max_f32_e32 v218, s57, v218
	v_max_f32_e32 v219, s57, v219
	v_lshlrev_b32_e32 v142, 16, v146
	v_and_b32_e32 v146, s56, v146
	v_lshlrev_b32_e32 v143, 16, v147
	v_and_b32_e32 v147, s56, v147
	v_lshlrev_b32_e32 v144, 16, v148
	v_and_b32_e32 v148, s56, v148
	v_lshlrev_b32_e32 v145, 16, v149
	v_and_b32_e32 v149, s56, v149
	v_max_f32_e32 v142, s57, v142
	v_max_f32_e32 v146, s57, v146
	v_max_f32_e32 v143, s57, v143
	v_max_f32_e32 v147, s57, v147
	v_max_f32_e32 v144, s57, v144
	v_max_f32_e32 v148, s57, v148
	v_max_f32_e32 v145, s57, v145
	v_max_f32_e32 v149, s57, v149
	v_rcp_f32_e32 v142, v142
	v_rcp_f32_e32 v146, v146
	v_rcp_f32_e32 v143, v143
	v_rcp_f32_e32 v147, v147
	v_rcp_f32_e32 v144, v144
	v_rcp_f32_e32 v148, v148
	v_rcp_f32_e32 v145, v145
	v_rcp_f32_e32 v149, v149
	v_mul_f32_e32 v184, v184, v142
	v_mul_f32_e32 v185, v185, v146
	v_mul_f32_e32 v186, v186, v143
	v_mul_f32_e32 v187, v187, v147
	v_mul_f32_e32 v188, v188, v144
	v_mul_f32_e32 v189, v189, v148
	v_mul_f32_e32 v218, v218, v145
	v_mul_f32_e32 v219, v219, v149
	v_pk_mul_f32 v[94:95], v[94:95], v[184:185]
	v_pk_mul_f32 v[96:97], v[96:97], v[186:187]
	v_pk_mul_f32 v[90:91], v[90:91], v[188:189]
	v_pk_mul_f32 v[92:93], v[92:93], v[218:219]
	global_load_dwordx4 v[134:137], v[130:131], off
	global_load_dwordx4 v[138:141], v[130:131], off offset:2048
	global_load_dwordx4 v[142:145], v[130:131], off offset:256
	global_load_dwordx4 v[146:149], v[130:131], off offset:2304
	v_lshl_add_u64 v[130:131], v[130:131], 0, s[58:59]
	s_waitcnt vmcnt(12)
; __device__ __forceinline__ float frcp(float x) { return __builtin_amdgcn_rcpf(x); }
; __device__ __forceinline__ u32x4 pack8(f32x4 a, f32x4 b) { u32x4 w; w.x = pk_bf16(a[0], a[1]); w.y = pk_bf16(a[2], a[3]); w.z = pk_bf16(b[0], b[1]); w.w = pk_bf16(b[2], b[3]); return w; }
; __device__ __forceinline__ void unpack8(u32x4 w, float* f) { f[0] = bf_lo(w.x); f[1] = bf_hi(w.x); f[2] = bf_lo(w.y); f[3] = bf_hi(w.y); f[4] = bf_lo(w.z); f[5] = bf_hi(w.z); f[6] = bf_lo(w.w); f[7] = bf_hi(w.w); }
; #define E2_LOAD(buf, g) do { const bf16_t* gp_ = G + (size_t)(rowb + ((g) >> 2) * 128 + ((g) & 3) * 16) * GATEW + br * 1024 + colb; \
;         L[buf][0] = *(const u32x4*)gp_; L[buf][1] = *(const u32x4*)(gp_ + 1024); L[buf][2] = *(const u32x4*)(gp_ + 128); L[buf][3] = *(const u32x4*)(gp_ + 128 + 1024); } while (0)
;     __device__ __forceinline__ bool operator()(f32x4 (&acc)[2][2][4][2], const pg8::Unit& u, int wr, int wc, int fr, int fq) const {
;     ...
;         for (int g = 0; g < 8; ++g) {
;             if (g < 7) E2_LOAD((g + 1) & 1, g + 1);
;             const int ai = g >> 2, m = g & 3, row = rowb + ai * 128 + m * 16;
; #pragma unroll
;             for (int bj = 0; bj < 2; ++bj) { const int col = colb + bj * 128; f32x4& v0 = acc[ai][bj][m][0]; f32x4& v1 = acc[ai][bj][m][1];
;                 float c[8], n[8]; unpack8(L[g & 1][2 * bj], c); unpack8(L[g & 1][2 * bj + 1], n); f32x4 o0, o1;
; #pragma unroll
;                 for (int j = 0; j < 8; ++j) { c[j] = fmaxf(c[j], 1e-30f); n[j] = last ? 1.0f : fmaxf(n[j], 1e-30f); }
; #pragma unroll
;                 for (int j = 0; j < 4; ++j) { v0[j] *= c[j] * frcp(n[j]); v1[j] *= c[4 + j] * frcp(n[4 + j]); }
; #pragma unroll
;                 for (int j = 0; j < 4; ++j) { o0[j] = v0[j] * n[j]; o1[j] = v1[j] * n[4 + j]; }
;                 *(u32x4*)(last ? MG + (size_t)row * DM + col : junk + (threadIdx.x & 511) * 8) = pack8(o0, o1); }
;             asm volatile("" ::: "memory");
	v_lshlrev_b32_e32 v184, 16, v150
	v_and_b32_e32 v185, s56, v150
	v_lshlrev_b32_e32 v186, 16, v151
	v_and_b32_e32 v187, s56, v151
	v_lshlrev_b32_e32 v188, 16, v152
	v_and_b32_e32 v189, s56, v152
	v_lshlrev_b32_e32 v218, 16, v153
	v_and_b32_e32 v219, s56, v153
	v_max_f32_e32 v184, s57, v184
	v_max_f32_e32 v185, s57, v185
	v_max_f32_e32 v186, s57, v186
	v_max_f32_e32 v187, s57, v187
	v_max_f32_e32 v188, s57, v188
	v_max_f32_e32 v189, s57, v189
	v_max_f32_e32 v218, s57, v218
	v_max_f32_e32 v219, s57, v219
	v_lshlrev_b32_e32 v150, 16, v154
	v_and_b32_e32 v154, s56, v154
	v_lshlrev_b32_e32 v151, 16, v155
	v_and_b32_e32 v155, s56, v155
	v_lshlrev_b32_e32 v152, 16, v156
	v_and_b32_e32 v156, s56, v156
	v_lshlrev_b32_e32 v153, 16, v157
	v_and_b32_e32 v157, s56, v157
	v_max_f32_e32 v150, s57, v150
	v_max_f32_e32 v154, s57, v154
	v_max_f32_e32 v151, s57, v151
	v_max_f32_e32 v155, s57, v155
	v_max_f32_e32 v152, s57, v152
	v_max_f32_e32 v156, s57, v156
	v_max_f32_e32 v153, s57, v153
	v_max_f32_e32 v157, s57, v157
	v_rcp_f32_e32 v150, v150
	v_rcp_f32_e32 v154, v154
	v_rcp_f32_e32 v151, v151
	v_rcp_f32_e32 v155, v155
	v_rcp_f32_e32 v152, v152
	v_rcp_f32_e32 v156, v156
	v_rcp_f32_e32 v153, v153
	v_rcp_f32_e32 v157, v157
	v_mul_f32_e32 v184, v184, v150
	v_mul_f32_e32 v185, v185, v154
	v_mul_f32_e32 v186, v186, v151
	v_mul_f32_e32 v187, v187, v155
	v_mul_f32_e32 v188, v188, v152
	v_mul_f32_e32 v189, v189, v156
	v_mul_f32_e32 v218, v218, v153
	v_mul_f32_e32 v219, v219, v157
	v_pk_mul_f32 v[118:119], v[118:119], v[184:185]
	v_pk_mul_f32 v[120:121], v[120:121], v[186:187]
	v_pk_mul_f32 v[114:115], v[114:115], v[188:189]
	v_pk_mul_f32 v[116:117], v[116:117], v[218:219]
	v_lshlrev_b32_e32 v184, 16, v158
	v_and_b32_e32 v185, s56, v158
	v_lshlrev_b32_e32 v186, 16, v159
	v_and_b32_e32 v187, s56, v159
	v_lshlrev_b32_e32 v188, 16, v160
	v_and_b32_e32 v189, s56, v160
	v_lshlrev_b32_e32 v218, 16, v161
	v_and_b32_e32 v219, s56, v161
	v_max_f32_e32 v184, s57, v184
	v_max_f32_e32 v185, s57, v185
	v_max_f32_e32 v186, s57, v186
	v_max_f32_e32 v187, s57, v187
	v_max_f32_e32 v188, s57, v188
	v_max_f32_e32 v189, s57, v189
	v_max_f32_e32 v218, s57, v218
	v_max_f32_e32 v219, s57, v219
	v_lshlrev_b32_e32 v158, 16, v162
	v_and_b32_e32 v162, s56, v162
	v_lshlrev_b32_e32 v159, 16, v163
	v_and_b32_e32 v163, s56, v163
	v_lshlrev_b32_e32 v160, 16, v164
	v_and_b32_e32 v164, s56, v164
	v_lshlrev_b32_e32 v161, 16, v165
	v_and_b32_e32 v165, s56, v165
	v_max_f32_e32 v158, s57, v158
	v_max_f32_e32 v162, s57, v162
	v_max_f32_e32 v159, s57, v159
	v_max_f32_e32 v163, s57, v163
	v_max_f32_e32 v160, s57, v160
	v_max_f32_e32 v164, s57, v164
	v_max_f32_e32 v161, s57, v161
	v_max_f32_e32 v165, s57, v165
	v_rcp_f32_e32 v158, v158
	v_rcp_f32_e32 v162, v162
	v_rcp_f32_e32 v159, v159
	v_rcp_f32_e32 v163, v163
	v_rcp_f32_e32 v160, v160
	v_rcp_f32_e32 v164, v164
	v_rcp_f32_e32 v161, v161
	v_rcp_f32_e32 v165, v165
	v_mul_f32_e32 v184, v184, v158
	v_mul_f32_e32 v185, v185, v162
	v_mul_f32_e32 v186, v186, v159
	v_mul_f32_e32 v187, v187, v163
	v_mul_f32_e32 v188, v188, v160
	v_mul_f32_e32 v189, v189, v164
	v_mul_f32_e32 v218, v218, v161
	v_mul_f32_e32 v219, v219, v165
	v_pk_mul_f32 v[86:87], v[86:87], v[184:185]
	v_pk_mul_f32 v[88:89], v[88:89], v[186:187]
	v_pk_mul_f32 v[82:83], v[82:83], v[188:189]
	v_pk_mul_f32 v[84:85], v[84:85], v[218:219]
	global_load_dwordx4 v[150:153], v[130:131], off
	global_load_dwordx4 v[154:157], v[130:131], off offset:2048
	global_load_dwordx4 v[158:161], v[130:131], off offset:256
	global_load_dwordx4 v[162:165], v[130:131], off offset:2304
	v_lshl_add_u64 v[130:131], v[130:131], 0, s[58:59]
	s_waitcnt vmcnt(12)
	v_lshlrev_b32_e32 v184, 16, v220
	v_and_b32_e32 v185, s56, v220
	v_lshlrev_b32_e32 v186, 16, v221
	v_and_b32_e32 v187, s56, v221
	v_lshlrev_b32_e32 v188, 16, v222
	v_and_b32_e32 v189, s56, v222
	v_lshlrev_b32_e32 v218, 16, v223
	v_and_b32_e32 v219, s56, v223
	v_max_f32_e32 v184, s57, v184
	v_max_f32_e32 v185, s57, v185
	v_max_f32_e32 v186, s57, v186
	v_max_f32_e32 v187, s57, v187
	v_max_f32_e32 v188, s57, v188
	v_max_f32_e32 v189, s57, v189
	v_max_f32_e32 v218, s57, v218
	v_max_f32_e32 v219, s57, v219
	v_lshlrev_b32_e32 v220, 16, v224
	v_and_b32_e32 v224, s56, v224
	v_lshlrev_b32_e32 v221, 16, v225
	v_and_b32_e32 v225, s56, v225
	v_lshlrev_b32_e32 v222, 16, v226
	v_and_b32_e32 v226, s56, v226
	v_lshlrev_b32_e32 v223, 16, v227
	v_and_b32_e32 v227, s56, v227
	v_max_f32_e32 v220, s57, v220
	v_max_f32_e32 v224, s57, v224
	v_max_f32_e32 v221, s57, v221
	v_max_f32_e32 v225, s57, v225
	v_max_f32_e32 v222, s57, v222
	v_max_f32_e32 v226, s57, v226
	v_max_f32_e32 v223, s57, v223
	v_max_f32_e32 v227, s57, v227
	v_rcp_f32_e32 v220, v220
	v_rcp_f32_e32 v224, v224
	v_rcp_f32_e32 v221, v221
	v_rcp_f32_e32 v225, v225
	v_rcp_f32_e32 v222, v222
	v_rcp_f32_e32 v226, v226
	v_rcp_f32_e32 v223, v223
	v_rcp_f32_e32 v227, v227
	v_mul_f32_e32 v184, v184, v220
	v_mul_f32_e32 v185, v185, v224
	v_mul_f32_e32 v186, v186, v221
	v_mul_f32_e32 v187, v187, v225
	v_mul_f32_e32 v188, v188, v222
	v_mul_f32_e32 v189, v189, v226
	v_mul_f32_e32 v218, v218, v223
	v_mul_f32_e32 v219, v219, v227
	v_pk_mul_f32 v[110:111], v[110:111], v[184:185]
	v_pk_mul_f32 v[112:113], v[112:113], v[186:187]
	v_pk_mul_f32 v[106:107], v[106:107], v[188:189]
	v_pk_mul_f32 v[108:109], v[108:109], v[218:219]
	v_lshlrev_b32_e32 v184, 16, v228
	v_and_b32_e32 v185, s56, v228
	v_lshlrev_b32_e32 v186, 16, v229
	v_and_b32_e32 v187, s56, v229
	v_lshlrev_b32_e32 v188, 16, v230
	v_and_b32_e32 v189, s56, v230
	v_lshlrev_b32_e32 v218, 16, v231
	v_and_b32_e32 v219, s56, v231
	v_max_f32_e32 v184, s57, v184
	v_max_f32_e32 v185, s57, v185
; __device__ __forceinline__ float frcp(float x) { return __builtin_amdgcn_rcpf(x); }
; __device__ __forceinline__ u32x4 pack8(f32x4 a, f32x4 b) { u32x4 w; w.x = pk_bf16(a[0], a[1]); w.y = pk_bf16(a[2], a[3]); w.z = pk_bf16(b[0], b[1]); w.w = pk_bf16(b[2], b[3]); return w; }
; __device__ __forceinline__ void unpack8(u32x4 w, float* f) { f[0] = bf_lo(w.x); f[1] = bf_hi(w.x); f[2] = bf_lo(w.y); f[3] = bf_hi(w.y); f[4] = bf_lo(w.z); f[5] = bf_hi(w.z); f[6] = bf_lo(w.w); f[7] = bf_hi(w.w); }
; #define E2_LOAD(buf, g) do { const bf16_t* gp_ = G + (size_t)(rowb + ((g) >> 2) * 128 + ((g) & 3) * 16) * GATEW + br * 1024 + colb; \
;         L[buf][0] = *(const u32x4*)gp_; L[buf][1] = *(const u32x4*)(gp_ + 1024); L[buf][2] = *(const u32x4*)(gp_ + 128); L[buf][3] = *(const u32x4*)(gp_ + 128 + 1024); } while (0)
;     __device__ __forceinline__ bool operator()(f32x4 (&acc)[2][2][4][2], const pg8::Unit& u, int wr, int wc, int fr, int fq) const {
;     ...
;         for (int g = 0; g < 8; ++g) {
;             if (g < 7) E2_LOAD((g + 1) & 1, g + 1);
;             const int ai = g >> 2, m = g & 3, row = rowb + ai * 128 + m * 16;
; #pragma unroll
;             for (int bj = 0; bj < 2; ++bj) { const int col = colb + bj * 128; f32x4& v0 = acc[ai][bj][m][0]; f32x4& v1 = acc[ai][bj][m][1];
;                 float c[8], n[8]; unpack8(L[g & 1][2 * bj], c); unpack8(L[g & 1][2 * bj + 1], n); f32x4 o0, o1;
; #pragma unroll
;                 for (int j = 0; j < 8; ++j) { c[j] = fmaxf(c[j], 1e-30f); n[j] = last ? 1.0f : fmaxf(n[j], 1e-30f); }
; #pragma unroll
;                 for (int j = 0; j < 4; ++j) { v0[j] *= c[j] * frcp(n[j]); v1[j] *= c[4 + j] * frcp(n[4 + j]); }
; #pragma unroll
;                 for (int j = 0; j < 4; ++j) { o0[j] = v0[j] * n[j]; o1[j] = v1[j] * n[4 + j]; }
;                 *(u32x4*)(last ? MG + (size_t)row * DM + col : junk + (threadIdx.x & 511) * 8) = pack8(o0, o1); }
;             asm volatile("" ::: "memory");
	v_max_f32_e32 v186, s57, v186
	v_max_f32_e32 v187, s57, v187
	v_max_f32_e32 v188, s57, v188
	v_max_f32_e32 v189, s57, v189
	v_max_f32_e32 v218, s57, v218
	v_max_f32_e32 v219, s57, v219
	v_lshlrev_b32_e32 v228, 16, v232
	v_and_b32_e32 v232, s56, v232
	v_lshlrev_b32_e32 v229, 16, v233
	v_and_b32_e32 v233, s56, v233
	v_lshlrev_b32_e32 v230, 16, v234
	v_and_b32_e32 v234, s56, v234
	v_lshlrev_b32_e32 v231, 16, v235
	v_and_b32_e32 v235, s56, v235
	v_max_f32_e32 v228, s57, v228
	v_max_f32_e32 v232, s57, v232
	v_max_f32_e32 v229, s57, v229
	v_max_f32_e32 v233, s57, v233
	v_max_f32_e32 v230, s57, v230
	v_max_f32_e32 v234, s57, v234
	v_max_f32_e32 v231, s57, v231
	v_max_f32_e32 v235, s57, v235
	v_rcp_f32_e32 v228, v228
	v_rcp_f32_e32 v232, v232
	v_rcp_f32_e32 v229, v229
	v_rcp_f32_e32 v233, v233
	v_rcp_f32_e32 v230, v230
	v_rcp_f32_e32 v234, v234
	v_rcp_f32_e32 v231, v231
	v_rcp_f32_e32 v235, v235
	v_mul_f32_e32 v184, v184, v228
	v_mul_f32_e32 v185, v185, v232
	v_mul_f32_e32 v186, v186, v229
	v_mul_f32_e32 v187, v187, v233
	v_mul_f32_e32 v188, v188, v230
	v_mul_f32_e32 v189, v189, v234
	v_mul_f32_e32 v218, v218, v231
	v_mul_f32_e32 v219, v219, v235
	v_pk_mul_f32 v[78:79], v[78:79], v[184:185]
	v_pk_mul_f32 v[80:81], v[80:81], v[186:187]
	v_pk_mul_f32 v[74:75], v[74:75], v[188:189]
	v_pk_mul_f32 v[76:77], v[76:77], v[218:219]
	global_load_dwordx4 v[220:223], v[130:131], off
	global_load_dwordx4 v[224:227], v[130:131], off offset:2048
	global_load_dwordx4 v[228:231], v[130:131], off offset:256
	global_load_dwordx4 v[232:235], v[130:131], off offset:2304
	v_lshl_add_u64 v[130:131], v[130:131], 0, s[58:59]
	s_waitcnt vmcnt(12)
	v_lshlrev_b32_e32 v184, 16, v242
	v_and_b32_e32 v185, s56, v242
	v_lshlrev_b32_e32 v186, 16, v243
	v_and_b32_e32 v187, s56, v243
	v_lshlrev_b32_e32 v188, 16, v244
	v_and_b32_e32 v189, s56, v244
	v_lshlrev_b32_e32 v218, 16, v245
	v_and_b32_e32 v219, s56, v245
	v_max_f32_e32 v184, s57, v184
	v_max_f32_e32 v185, s57, v185
	v_max_f32_e32 v186, s57, v186
	v_max_f32_e32 v187, s57, v187
	v_max_f32_e32 v188, s57, v188
	v_max_f32_e32 v189, s57, v189
	v_max_f32_e32 v218, s57, v218
	v_max_f32_e32 v219, s57, v219
	v_lshlrev_b32_e32 v242, 16, v246
	v_and_b32_e32 v246, s56, v246
	v_lshlrev_b32_e32 v243, 16, v247
	v_and_b32_e32 v247, s56, v247
	v_lshlrev_b32_e32 v244, 16, v248
	v_and_b32_e32 v248, s56, v248
	v_lshlrev_b32_e32 v245, 16, v249
	v_and_b32_e32 v249, s56, v249
	v_max_f32_e32 v242, s57, v242
	v_max_f32_e32 v246, s57, v246
	v_max_f32_e32 v243, s57, v243
	v_max_f32_e32 v247, s57, v247
	v_max_f32_e32 v244, s57, v244
	v_max_f32_e32 v248, s57, v248
	v_max_f32_e32 v245, s57, v245
	v_max_f32_e32 v249, s57, v249
	v_rcp_f32_e32 v242, v242
	v_rcp_f32_e32 v246, v246
	v_rcp_f32_e32 v243, v243
	v_rcp_f32_e32 v247, v247
	v_rcp_f32_e32 v244, v244
	v_rcp_f32_e32 v248, v248
	v_rcp_f32_e32 v245, v245
	v_rcp_f32_e32 v249, v249
	v_mul_f32_e32 v184, v184, v242
	v_mul_f32_e32 v185, v185, v246
	v_mul_f32_e32 v186, v186, v243
	v_mul_f32_e32 v187, v187, v247
	v_mul_f32_e32 v188, v188, v244
	v_mul_f32_e32 v189, v189, v248
	v_mul_f32_e32 v218, v218, v245
	v_mul_f32_e32 v219, v219, v249
	v_pk_mul_f32 v[102:103], v[102:103], v[184:185]
	v_pk_mul_f32 v[104:105], v[104:105], v[186:187]
	v_pk_mul_f32 v[98:99], v[98:99], v[188:189]
	v_pk_mul_f32 v[100:101], v[100:101], v[218:219]
	v_lshlrev_b32_e32 v184, 16, v210
	v_and_b32_e32 v185, s56, v210
	v_lshlrev_b32_e32 v186, 16, v211
	v_and_b32_e32 v187, s56, v211
	v_lshlrev_b32_e32 v188, 16, v212
	v_and_b32_e32 v189, s56, v212
	v_lshlrev_b32_e32 v218, 16, v213
	v_and_b32_e32 v219, s56, v213
	v_max_f32_e32 v184, s57, v184
	v_max_f32_e32 v185, s57, v185
	v_max_f32_e32 v186, s57, v186
	v_max_f32_e32 v187, s57, v187
	v_max_f32_e32 v188, s57, v188
	v_max_f32_e32 v189, s57, v189
	v_max_f32_e32 v218, s57, v218
	v_max_f32_e32 v219, s57, v219
	v_lshlrev_b32_e32 v210, 16, v214
	v_and_b32_e32 v214, s56, v214
	v_lshlrev_b32_e32 v211, 16, v215
	v_and_b32_e32 v215, s56, v215
	v_lshlrev_b32_e32 v212, 16, v216
	v_and_b32_e32 v216, s56, v216
	v_lshlrev_b32_e32 v213, 16, v217
	v_and_b32_e32 v217, s56, v217
	v_max_f32_e32 v210, s57, v210
	v_max_f32_e32 v214, s57, v214
	v_max_f32_e32 v211, s57, v211
	v_max_f32_e32 v215, s57, v215
	v_max_f32_e32 v212, s57, v212
	v_max_f32_e32 v216, s57, v216
	v_max_f32_e32 v213, s57, v213
	v_max_f32_e32 v217, s57, v217
	v_rcp_f32_e32 v210, v210
	v_rcp_f32_e32 v214, v214
	v_rcp_f32_e32 v211, v211
	v_rcp_f32_e32 v215, v215
	v_rcp_f32_e32 v212, v212
	v_rcp_f32_e32 v216, v216
	v_rcp_f32_e32 v213, v213
	v_rcp_f32_e32 v217, v217
	v_mul_f32_e32 v184, v184, v210
	v_mul_f32_e32 v185, v185, v214
	v_mul_f32_e32 v186, v186, v211
	v_mul_f32_e32 v187, v187, v215
	v_mul_f32_e32 v188, v188, v212
	v_mul_f32_e32 v189, v189, v216
	v_mul_f32_e32 v218, v218, v213
	v_mul_f32_e32 v219, v219, v217
	v_pk_mul_f32 v[70:71], v[70:71], v[184:185]
	v_pk_mul_f32 v[72:73], v[72:73], v[186:187]
	v_pk_mul_f32 v[66:67], v[66:67], v[188:189]
	v_pk_mul_f32 v[68:69], v[68:69], v[218:219]
	global_load_dwordx4 v[242:245], v[130:131], off
	global_load_dwordx4 v[246:249], v[130:131], off offset:2048
	global_load_dwordx4 v[210:213], v[130:131], off offset:256
	global_load_dwordx4 v[214:217], v[130:131], off offset:2304
	s_waitcnt vmcnt(12)
; __device__ __forceinline__ float frcp(float x) { return __builtin_amdgcn_rcpf(x); }
; __device__ __forceinline__ u32x4 pack8(f32x4 a, f32x4 b) { u32x4 w; w.x = pk_bf16(a[0], a[1]); w.y = pk_bf16(a[2], a[3]); w.z = pk_bf16(b[0], b[1]); w.w = pk_bf16(b[2], b[3]); return w; }
; __device__ __forceinline__ void unpack8(u32x4 w, float* f) { f[0] = bf_lo(w.x); f[1] = bf_hi(w.x); f[2] = bf_lo(w.y); f[3] = bf_hi(w.y); f[4] = bf_lo(w.z); f[5] = bf_hi(w.z); f[6] = bf_lo(w.w); f[7] = bf_hi(w.w); }
; #define E2_LOAD(buf, g) do { const bf16_t* gp_ = G + (size_t)(rowb + ((g) >> 2) * 128 + ((g) & 3) * 16) * GATEW + br * 1024 + colb; \
;         L[buf][0] = *(const u32x4*)gp_; L[buf][1] = *(const u32x4*)(gp_ + 1024); L[buf][2] = *(const u32x4*)(gp_ + 128); L[buf][3] = *(const u32x4*)(gp_ + 128 + 1024); } while (0)
;     __device__ __forceinline__ bool operator()(f32x4 (&acc)[2][2][4][2], const pg8::Unit& u, int wr, int wc, int fr, int fq) const {
;     ...
;         for (int g = 0; g < 8; ++g) {
;             if (g < 7) E2_LOAD((g + 1) & 1, g + 1);
;             const int ai = g >> 2, m = g & 3, row = rowb + ai * 128 + m * 16;
; #pragma unroll
;             for (int bj = 0; bj < 2; ++bj) { const int col = colb + bj * 128; f32x4& v0 = acc[ai][bj][m][0]; f32x4& v1 = acc[ai][bj][m][1];
;                 float c[8], n[8]; unpack8(L[g & 1][2 * bj], c); unpack8(L[g & 1][2 * bj + 1], n); f32x4 o0, o1;
; #pragma unroll
;                 for (int j = 0; j < 8; ++j) { c[j] = fmaxf(c[j], 1e-30f); n[j] = last ? 1.0f : fmaxf(n[j], 1e-30f); }
; #pragma unroll
;                 for (int j = 0; j < 4; ++j) { v0[j] *= c[j] * frcp(n[j]); v1[j] *= c[4 + j] * frcp(n[4 + j]); }
; #pragma unroll
;                 for (int j = 0; j < 4; ++j) { o0[j] = v0[j] * n[j]; o1[j] = v1[j] * n[4 + j]; }
;                 *(u32x4*)(last ? MG + (size_t)row * DM + col : junk + (threadIdx.x & 511) * 8) = pack8(o0, o1); }
;             asm volatile("" ::: "memory");
	v_lshlrev_b32_e32 v184, 16, v134
	v_and_b32_e32 v185, s56, v134
	v_lshlrev_b32_e32 v186, 16, v135
	v_and_b32_e32 v187, s56, v135
	v_lshlrev_b32_e32 v188, 16, v136
	v_and_b32_e32 v189, s56, v136
	v_lshlrev_b32_e32 v218, 16, v137
	v_and_b32_e32 v219, s56, v137
	v_max_f32_e32 v184, s57, v184
	v_max_f32_e32 v185, s57, v185
	v_max_f32_e32 v186, s57, v186
	v_max_f32_e32 v187, s57, v187
	v_max_f32_e32 v188, s57, v188
	v_max_f32_e32 v189, s57, v189
	v_max_f32_e32 v218, s57, v218
	v_max_f32_e32 v219, s57, v219
	v_lshlrev_b32_e32 v134, 16, v138
	v_and_b32_e32 v138, s56, v138
	v_lshlrev_b32_e32 v135, 16, v139
	v_and_b32_e32 v139, s56, v139
	v_lshlrev_b32_e32 v136, 16, v140
	v_and_b32_e32 v140, s56, v140
	v_lshlrev_b32_e32 v137, 16, v141
	v_and_b32_e32 v141, s56, v141
	v_max_f32_e32 v134, s57, v134
	v_max_f32_e32 v138, s57, v138
	v_max_f32_e32 v135, s57, v135
	v_max_f32_e32 v139, s57, v139
	v_max_f32_e32 v136, s57, v136
	v_max_f32_e32 v140, s57, v140
	v_max_f32_e32 v137, s57, v137
	v_max_f32_e32 v141, s57, v141
	v_rcp_f32_e32 v134, v134
	v_rcp_f32_e32 v138, v138
	v_rcp_f32_e32 v135, v135
	v_rcp_f32_e32 v139, v139
	v_rcp_f32_e32 v136, v136
	v_rcp_f32_e32 v140, v140
	v_rcp_f32_e32 v137, v137
	v_rcp_f32_e32 v141, v141
	v_mul_f32_e32 v184, v184, v134
	v_mul_f32_e32 v185, v185, v138
	v_mul_f32_e32 v186, v186, v135
	v_mul_f32_e32 v187, v187, v139
	v_mul_f32_e32 v188, v188, v136
	v_mul_f32_e32 v189, v189, v140
	v_mul_f32_e32 v218, v218, v137
	v_mul_f32_e32 v219, v219, v141
	v_pk_mul_f32 v[62:63], v[62:63], v[184:185]
	v_pk_mul_f32 v[64:65], v[64:65], v[186:187]
	v_pk_mul_f32 v[58:59], v[58:59], v[188:189]
	v_pk_mul_f32 v[60:61], v[60:61], v[218:219]
	v_lshlrev_b32_e32 v184, 16, v142
	v_and_b32_e32 v185, s56, v142
	v_lshlrev_b32_e32 v186, 16, v143
	v_and_b32_e32 v187, s56, v143
	v_lshlrev_b32_e32 v188, 16, v144
	v_and_b32_e32 v189, s56, v144
	v_lshlrev_b32_e32 v218, 16, v145
	v_and_b32_e32 v219, s56, v145
	v_max_f32_e32 v184, s57, v184
	v_max_f32_e32 v185, s57, v185
	v_max_f32_e32 v186, s57, v186
	v_max_f32_e32 v187, s57, v187
	v_max_f32_e32 v188, s57, v188
	v_max_f32_e32 v189, s57, v189
	v_max_f32_e32 v218, s57, v218
	v_max_f32_e32 v219, s57, v219
	v_lshlrev_b32_e32 v142, 16, v146
	v_and_b32_e32 v146, s56, v146
	v_lshlrev_b32_e32 v143, 16, v147
	v_and_b32_e32 v147, s56, v147
	v_lshlrev_b32_e32 v144, 16, v148
	v_and_b32_e32 v148, s56, v148
	v_lshlrev_b32_e32 v145, 16, v149
	v_and_b32_e32 v149, s56, v149
	v_max_f32_e32 v142, s57, v142
	v_max_f32_e32 v146, s57, v146
	v_max_f32_e32 v143, s57, v143
	v_max_f32_e32 v147, s57, v147
	v_max_f32_e32 v144, s57, v144
	v_max_f32_e32 v148, s57, v148
	v_max_f32_e32 v145, s57, v145
	v_max_f32_e32 v149, s57, v149
	v_rcp_f32_e32 v142, v142
	v_rcp_f32_e32 v146, v146
	v_rcp_f32_e32 v143, v143
	v_rcp_f32_e32 v147, v147
	v_rcp_f32_e32 v144, v144
	v_rcp_f32_e32 v148, v148
	v_rcp_f32_e32 v145, v145
	v_rcp_f32_e32 v149, v149
	v_mul_f32_e32 v184, v184, v142
	v_mul_f32_e32 v185, v185, v146
	v_mul_f32_e32 v186, v186, v143
	v_mul_f32_e32 v187, v187, v147
	v_mul_f32_e32 v188, v188, v144
	v_mul_f32_e32 v189, v189, v148
	v_mul_f32_e32 v218, v218, v145
	v_mul_f32_e32 v219, v219, v149
	v_pk_mul_f32 v[30:31], v[30:31], v[184:185]
	v_pk_mul_f32 v[32:33], v[32:33], v[186:187]
	v_pk_mul_f32 v[26:27], v[26:27], v[188:189]
	v_pk_mul_f32 v[28:29], v[28:29], v[218:219]
	s_waitcnt vmcnt(8)
	v_lshlrev_b32_e32 v184, 16, v150
	v_and_b32_e32 v185, s56, v150
	v_lshlrev_b32_e32 v186, 16, v151
	v_and_b32_e32 v187, s56, v151
	v_lshlrev_b32_e32 v188, 16, v152
	v_and_b32_e32 v189, s56, v152
	v_lshlrev_b32_e32 v218, 16, v153
	v_and_b32_e32 v219, s56, v153
	v_max_f32_e32 v184, s57, v184
	v_max_f32_e32 v185, s57, v185
	v_max_f32_e32 v186, s57, v186
	v_max_f32_e32 v187, s57, v187
	v_max_f32_e32 v188, s57, v188
	v_max_f32_e32 v189, s57, v189
	v_max_f32_e32 v218, s57, v218
	v_max_f32_e32 v219, s57, v219
	v_lshlrev_b32_e32 v150, 16, v154
	v_and_b32_e32 v154, s56, v154
	v_lshlrev_b32_e32 v151, 16, v155
	v_and_b32_e32 v155, s56, v155
	v_lshlrev_b32_e32 v152, 16, v156
	v_and_b32_e32 v156, s56, v156
	v_lshlrev_b32_e32 v153, 16, v157
	v_and_b32_e32 v157, s56, v157
	v_max_f32_e32 v150, s57, v150
	v_max_f32_e32 v154, s57, v154
	v_max_f32_e32 v151, s57, v151
	v_max_f32_e32 v155, s57, v155
	v_max_f32_e32 v152, s57, v152
	v_max_f32_e32 v156, s57, v156
	v_max_f32_e32 v153, s57, v153
	v_max_f32_e32 v157, s57, v157
	v_rcp_f32_e32 v150, v150
	v_rcp_f32_e32 v154, v154
	v_rcp_f32_e32 v151, v151
	v_rcp_f32_e32 v155, v155
	v_rcp_f32_e32 v152, v152
	v_rcp_f32_e32 v156, v156
	v_rcp_f32_e32 v153, v153
	v_rcp_f32_e32 v157, v157
	v_mul_f32_e32 v184, v184, v150
	v_mul_f32_e32 v185, v185, v154
	v_mul_f32_e32 v186, v186, v151
	v_mul_f32_e32 v187, v187, v155
	v_mul_f32_e32 v188, v188, v152
	v_mul_f32_e32 v189, v189, v156
	v_mul_f32_e32 v218, v218, v153
	v_mul_f32_e32 v219, v219, v157
	v_pk_mul_f32 v[54:55], v[54:55], v[184:185]
	v_pk_mul_f32 v[56:57], v[56:57], v[186:187]
	v_pk_mul_f32 v[50:51], v[50:51], v[188:189]
	v_pk_mul_f32 v[52:53], v[52:53], v[218:219]
	v_lshlrev_b32_e32 v184, 16, v158
	v_and_b32_e32 v185, s56, v158
	v_lshlrev_b32_e32 v186, 16, v159
	v_and_b32_e32 v187, s56, v159
	v_lshlrev_b32_e32 v188, 16, v160
	v_and_b32_e32 v189, s56, v160
	v_lshlrev_b32_e32 v218, 16, v161
	v_and_b32_e32 v219, s56, v161
	v_max_f32_e32 v184, s57, v184
	v_max_f32_e32 v185, s57, v185
	v_max_f32_e32 v186, s57, v186
	v_max_f32_e32 v187, s57, v187
	v_max_f32_e32 v188, s57, v188
	v_max_f32_e32 v189, s57, v189
	v_max_f32_e32 v218, s57, v218
	v_max_f32_e32 v219, s57, v219
	v_lshlrev_b32_e32 v158, 16, v162
	v_and_b32_e32 v162, s56, v162
	v_lshlrev_b32_e32 v159, 16, v163
	v_and_b32_e32 v163, s56, v163
	v_lshlrev_b32_e32 v160, 16, v164
	v_and_b32_e32 v164, s56, v164
	v_lshlrev_b32_e32 v161, 16, v165
	v_and_b32_e32 v165, s56, v165
	v_max_f32_e32 v158, s57, v158
	v_max_f32_e32 v162, s57, v162
	v_max_f32_e32 v159, s57, v159
	v_max_f32_e32 v163, s57, v163
	v_max_f32_e32 v160, s57, v160
	v_max_f32_e32 v164, s57, v164
	v_max_f32_e32 v161, s57, v161
	v_max_f32_e32 v165, s57, v165
	v_rcp_f32_e32 v158, v158
	v_rcp_f32_e32 v162, v162
	v_rcp_f32_e32 v159, v159
	v_rcp_f32_e32 v163, v163
	v_rcp_f32_e32 v160, v160
	v_rcp_f32_e32 v164, v164
	v_rcp_f32_e32 v161, v161
	v_rcp_f32_e32 v165, v165
	v_mul_f32_e32 v184, v184, v158
	v_mul_f32_e32 v185, v185, v162
	v_mul_f32_e32 v186, v186, v159
	v_mul_f32_e32 v187, v187, v163
	v_mul_f32_e32 v188, v188, v160
	v_mul_f32_e32 v189, v189, v164
	v_mul_f32_e32 v218, v218, v161
	v_mul_f32_e32 v219, v219, v165
	v_pk_mul_f32 v[22:23], v[22:23], v[184:185]
	v_pk_mul_f32 v[24:25], v[24:25], v[186:187]
	v_pk_mul_f32 v[18:19], v[18:19], v[188:189]
	v_pk_mul_f32 v[20:21], v[20:21], v[218:219]
	s_waitcnt vmcnt(4)
; __device__ __forceinline__ float frcp(float x) { return __builtin_amdgcn_rcpf(x); }
; __device__ __forceinline__ u32x4 pack8(f32x4 a, f32x4 b) { u32x4 w; w.x = pk_bf16(a[0], a[1]); w.y = pk_bf16(a[2], a[3]); w.z = pk_bf16(b[0], b[1]); w.w = pk_bf16(b[2], b[3]); return w; }
; __device__ __forceinline__ void unpack8(u32x4 w, float* f) { f[0] = bf_lo(w.x); f[1] = bf_hi(w.x); f[2] = bf_lo(w.y); f[3] = bf_hi(w.y); f[4] = bf_lo(w.z); f[5] = bf_hi(w.z); f[6] = bf_lo(w.w); f[7] = bf_hi(w.w); }
; #define E2_LOAD(buf, g) do { const bf16_t* gp_ = G + (size_t)(rowb + ((g) >> 2) * 128 + ((g) & 3) * 16) * GATEW + br * 1024 + colb; \
;         L[buf][0] = *(const u32x4*)gp_; L[buf][1] = *(const u32x4*)(gp_ + 1024); L[buf][2] = *(const u32x4*)(gp_ + 128); L[buf][3] = *(const u32x4*)(gp_ + 128 + 1024); } while (0)
;     __device__ __forceinline__ bool operator()(f32x4 (&acc)[2][2][4][2], const pg8::Unit& u, int wr, int wc, int fr, int fq) const {
;     ...
;         for (int g = 0; g < 8; ++g) {
;             if (g < 7) E2_LOAD((g + 1) & 1, g + 1);
;             const int ai = g >> 2, m = g & 3, row = rowb + ai * 128 + m * 16;
; #pragma unroll
;             for (int bj = 0; bj < 2; ++bj) { const int col = colb + bj * 128; f32x4& v0 = acc[ai][bj][m][0]; f32x4& v1 = acc[ai][bj][m][1];
;                 float c[8], n[8]; unpack8(L[g & 1][2 * bj], c); unpack8(L[g & 1][2 * bj + 1], n); f32x4 o0, o1;
; #pragma unroll
;                 for (int j = 0; j < 8; ++j) { c[j] = fmaxf(c[j], 1e-30f); n[j] = last ? 1.0f : fmaxf(n[j], 1e-30f); }
; #pragma unroll
;                 for (int j = 0; j < 4; ++j) { v0[j] *= c[j] * frcp(n[j]); v1[j] *= c[4 + j] * frcp(n[4 + j]); }
; #pragma unroll
;                 for (int j = 0; j < 4; ++j) { o0[j] = v0[j] * n[j]; o1[j] = v1[j] * n[4 + j]; }
;                 *(u32x4*)(last ? MG + (size_t)row * DM + col : junk + (threadIdx.x & 511) * 8) = pack8(o0, o1); }
;             asm volatile("" ::: "memory");
	v_lshlrev_b32_e32 v184, 16, v220
	v_and_b32_e32 v185, s56, v220
	v_lshlrev_b32_e32 v186, 16, v221
	v_and_b32_e32 v187, s56, v221
	v_lshlrev_b32_e32 v188, 16, v222
	v_and_b32_e32 v189, s56, v222
	v_lshlrev_b32_e32 v218, 16, v223
	v_and_b32_e32 v219, s56, v223
	v_max_f32_e32 v184, s57, v184
	v_max_f32_e32 v185, s57, v185
	v_max_f32_e32 v186, s57, v186
	v_max_f32_e32 v187, s57, v187
	v_max_f32_e32 v188, s57, v188
	v_max_f32_e32 v189, s57, v189
	v_max_f32_e32 v218, s57, v218
	v_max_f32_e32 v219, s57, v219
	v_lshlrev_b32_e32 v220, 16, v224
	v_and_b32_e32 v224, s56, v224
	v_lshlrev_b32_e32 v221, 16, v225
	v_and_b32_e32 v225, s56, v225
	v_lshlrev_b32_e32 v222, 16, v226
	v_and_b32_e32 v226, s56, v226
	v_lshlrev_b32_e32 v223, 16, v227
	v_and_b32_e32 v227, s56, v227
	v_max_f32_e32 v220, s57, v220
	v_max_f32_e32 v224, s57, v224
	v_max_f32_e32 v221, s57, v221
	v_max_f32_e32 v225, s57, v225
	v_max_f32_e32 v222, s57, v222
	v_max_f32_e32 v226, s57, v226
	v_max_f32_e32 v223, s57, v223
	v_max_f32_e32 v227, s57, v227
	v_rcp_f32_e32 v220, v220
	v_rcp_f32_e32 v224, v224
	v_rcp_f32_e32 v221, v221
	v_rcp_f32_e32 v225, v225
	v_rcp_f32_e32 v222, v222
	v_rcp_f32_e32 v226, v226
	v_rcp_f32_e32 v223, v223
	v_rcp_f32_e32 v227, v227
	v_mul_f32_e32 v184, v184, v220
	v_mul_f32_e32 v185, v185, v224
	v_mul_f32_e32 v186, v186, v221
	v_mul_f32_e32 v187, v187, v225
	v_mul_f32_e32 v188, v188, v222
	v_mul_f32_e32 v189, v189, v226
	v_mul_f32_e32 v218, v218, v223
	v_mul_f32_e32 v219, v219, v227
	v_pk_mul_f32 v[46:47], v[46:47], v[184:185]
	v_pk_mul_f32 v[48:49], v[48:49], v[186:187]
	v_pk_mul_f32 v[42:43], v[42:43], v[188:189]
	v_pk_mul_f32 v[44:45], v[44:45], v[218:219]
	v_lshlrev_b32_e32 v184, 16, v228
	v_and_b32_e32 v185, s56, v228
	v_lshlrev_b32_e32 v186, 16, v229
	v_and_b32_e32 v187, s56, v229
	v_lshlrev_b32_e32 v188, 16, v230
	v_and_b32_e32 v189, s56, v230
	v_lshlrev_b32_e32 v218, 16, v231
	v_and_b32_e32 v219, s56, v231
	v_max_f32_e32 v184, s57, v184
	v_max_f32_e32 v185, s57, v185
	v_max_f32_e32 v186, s57, v186
	v_max_f32_e32 v187, s57, v187
	v_max_f32_e32 v188, s57, v188
	v_max_f32_e32 v189, s57, v189
	v_max_f32_e32 v218, s57, v218
	v_max_f32_e32 v219, s57, v219
	v_lshlrev_b32_e32 v228, 16, v232
	v_and_b32_e32 v232, s56, v232
	v_lshlrev_b32_e32 v229, 16, v233
	v_and_b32_e32 v233, s56, v233
	v_lshlrev_b32_e32 v230, 16, v234
	v_and_b32_e32 v234, s56, v234
	v_lshlrev_b32_e32 v231, 16, v235
	v_and_b32_e32 v235, s56, v235
	v_max_f32_e32 v228, s57, v228
	v_max_f32_e32 v232, s57, v232
	v_max_f32_e32 v229, s57, v229
	v_max_f32_e32 v233, s57, v233
	v_max_f32_e32 v230, s57, v230
	v_max_f32_e32 v234, s57, v234
	v_max_f32_e32 v231, s57, v231
	v_max_f32_e32 v235, s57, v235
	v_rcp_f32_e32 v228, v228
	v_rcp_f32_e32 v232, v232
	v_rcp_f32_e32 v229, v229
	v_rcp_f32_e32 v233, v233
	v_rcp_f32_e32 v230, v230
	v_rcp_f32_e32 v234, v234
	v_rcp_f32_e32 v231, v231
	v_rcp_f32_e32 v235, v235
	v_mul_f32_e32 v184, v184, v228
	v_mul_f32_e32 v185, v185, v232
	v_mul_f32_e32 v186, v186, v229
	v_mul_f32_e32 v187, v187, v233
	v_mul_f32_e32 v188, v188, v230
	v_mul_f32_e32 v189, v189, v234
	v_mul_f32_e32 v218, v218, v231
	v_mul_f32_e32 v219, v219, v235
	v_pk_mul_f32 v[14:15], v[14:15], v[184:185]
	v_pk_mul_f32 v[16:17], v[16:17], v[186:187]
	v_pk_mul_f32 v[10:11], v[10:11], v[188:189]
	v_pk_mul_f32 v[12:13], v[12:13], v[218:219]
	s_waitcnt vmcnt(0)
	v_lshlrev_b32_e32 v184, 16, v242
	v_and_b32_e32 v185, s56, v242
	v_lshlrev_b32_e32 v186, 16, v243
	v_and_b32_e32 v187, s56, v243
	v_lshlrev_b32_e32 v188, 16, v244
	v_and_b32_e32 v189, s56, v244
	v_lshlrev_b32_e32 v218, 16, v245
	v_and_b32_e32 v219, s56, v245
	v_max_f32_e32 v184, s57, v184
	v_max_f32_e32 v185, s57, v185
	v_max_f32_e32 v186, s57, v186
	v_max_f32_e32 v187, s57, v187
	v_max_f32_e32 v188, s57, v188
	v_max_f32_e32 v189, s57, v189
	v_max_f32_e32 v218, s57, v218
	v_max_f32_e32 v219, s57, v219
	v_lshlrev_b32_e32 v242, 16, v246
	v_and_b32_e32 v246, s56, v246
	v_lshlrev_b32_e32 v243, 16, v247
	v_and_b32_e32 v247, s56, v247
	v_lshlrev_b32_e32 v244, 16, v248
	v_and_b32_e32 v248, s56, v248
	v_lshlrev_b32_e32 v245, 16, v249
	v_and_b32_e32 v249, s56, v249
	v_max_f32_e32 v242, s57, v242
	v_max_f32_e32 v246, s57, v246
	v_max_f32_e32 v243, s57, v243
	v_max_f32_e32 v247, s57, v247
	v_max_f32_e32 v244, s57, v244
	v_max_f32_e32 v248, s57, v248
	v_max_f32_e32 v245, s57, v245
	v_max_f32_e32 v249, s57, v249
	v_rcp_f32_e32 v242, v242
	v_rcp_f32_e32 v246, v246
	v_rcp_f32_e32 v243, v243
	v_rcp_f32_e32 v247, v247
	v_rcp_f32_e32 v244, v244
	v_rcp_f32_e32 v248, v248
	v_rcp_f32_e32 v245, v245
	v_rcp_f32_e32 v249, v249
	v_mul_f32_e32 v184, v184, v242
	v_mul_f32_e32 v185, v185, v246
	v_mul_f32_e32 v186, v186, v243
	v_mul_f32_e32 v187, v187, v247
	v_mul_f32_e32 v188, v188, v244
	v_mul_f32_e32 v189, v189, v248
	v_mul_f32_e32 v218, v218, v245
	v_mul_f32_e32 v219, v219, v249
	v_pk_mul_f32 v[38:39], v[38:39], v[184:185]
	v_pk_mul_f32 v[40:41], v[40:41], v[186:187]
	v_pk_mul_f32 v[34:35], v[34:35], v[188:189]
	v_pk_mul_f32 v[36:37], v[36:37], v[218:219]
	v_lshlrev_b32_e32 v184, 16, v210
	v_and_b32_e32 v185, s56, v210
	v_lshlrev_b32_e32 v186, 16, v211
	v_and_b32_e32 v187, s56, v211
	v_lshlrev_b32_e32 v188, 16, v212
	v_and_b32_e32 v189, s56, v212
	v_lshlrev_b32_e32 v218, 16, v213
	v_and_b32_e32 v219, s56, v213
	v_max_f32_e32 v184, s57, v184
	v_max_f32_e32 v185, s57, v185
	v_max_f32_e32 v186, s57, v186
	v_max_f32_e32 v187, s57, v187
	v_max_f32_e32 v188, s57, v188
	v_max_f32_e32 v189, s57, v189
	v_max_f32_e32 v218, s57, v218
	v_max_f32_e32 v219, s57, v219
	v_lshlrev_b32_e32 v210, 16, v214
	v_and_b32_e32 v214, s56, v214
	v_lshlrev_b32_e32 v211, 16, v215
	v_and_b32_e32 v215, s56, v215
	v_lshlrev_b32_e32 v212, 16, v216
	v_and_b32_e32 v216, s56, v216
	v_lshlrev_b32_e32 v213, 16, v217
	v_and_b32_e32 v217, s56, v217
	v_max_f32_e32 v210, s57, v210
	v_max_f32_e32 v214, s57, v214
	v_max_f32_e32 v211, s57, v211
	v_max_f32_e32 v215, s57, v215
	v_max_f32_e32 v212, s57, v212
	v_max_f32_e32 v216, s57, v216
	v_max_f32_e32 v213, s57, v213
	v_max_f32_e32 v217, s57, v217
	v_rcp_f32_e32 v210, v210
	v_rcp_f32_e32 v214, v214
	v_rcp_f32_e32 v211, v211
	v_rcp_f32_e32 v215, v215
	v_rcp_f32_e32 v212, v212
	v_rcp_f32_e32 v216, v216
	v_rcp_f32_e32 v213, v213
	v_rcp_f32_e32 v217, v217
	v_mul_f32_e32 v184, v184, v210
	v_mul_f32_e32 v185, v185, v214
	v_mul_f32_e32 v186, v186, v211
	v_mul_f32_e32 v187, v187, v215
	v_mul_f32_e32 v188, v188, v212
	v_mul_f32_e32 v189, v189, v216
	v_mul_f32_e32 v218, v218, v213
	v_mul_f32_e32 v219, v219, v217
	v_pk_mul_f32 v[6:7], v[6:7], v[184:185]
	v_pk_mul_f32 v[8:9], v[8:9], v[186:187]
	v_pk_mul_f32 v[2:3], v[2:3], v[188:189]
	v_pk_mul_f32 v[4:5], v[4:5], v[218:219]
	s_branch .Le2_done
; __device__ __forceinline__ u32x4 pack8(f32x4 a, f32x4 b) { u32x4 w; w.x = pk_bf16(a[0], a[1]); w.y = pk_bf16(a[2], a[3]); w.z = pk_bf16(b[0], b[1]); w.w = pk_bf16(b[2], b[3]); return w; }
;     __device__ __forceinline__ bool operator()(f32x4 (&acc)[2][2][4][2], const pg8::Unit& u, int wr, int wc, int fr, int fq) const {
;     ...
;                 *(u32x4*)(last ? MG + (size_t)row * DM + col : junk + (threadIdx.x & 511) * 8) = pack8(o0, o1); }
;             asm volatile("" ::: "memory");
;         }
;     ...
;         return last;
	s_nop 0
	s_nop 0
	s_nop 0
	s_nop 0
	s_nop 0
	s_nop 0
	s_nop 0
	s_nop 0
	s_nop 0
	s_nop 0
	s_nop 0
	s_nop 0
	s_nop 0
	s_nop 0
	s_nop 0
	s_nop 0
	s_nop 0
	s_nop 0
	s_nop 0
	s_nop 0
	s_nop 0
	s_nop 0
	s_nop 0
	s_nop 0
	s_nop 0
	s_nop 0
	s_nop 0
	s_nop 0
	s_nop 0
	s_nop 0
	s_nop 0
	s_nop 0
	s_nop 0
	s_nop 0
	s_nop 0
	s_nop 0
	s_nop 0
	s_nop 0
	s_nop 0
	s_nop 0
	s_nop 0
	s_nop 0
	s_nop 0
	s_nop 0
	s_nop 0
	s_nop 0
	s_nop 0
	s_nop 0
	s_nop 0
	s_nop 0
	s_nop 0
	s_nop 0
	s_nop 0
	s_nop 0
	s_nop 0
	s_nop 0
	s_nop 0
	s_nop 0
	s_nop 0
	s_nop 0
	s_nop 0
	s_nop 0
	s_nop 0
	s_nop 0
	s_nop 0
	s_nop 0
	s_nop 0
	s_nop 0
	s_nop 0
	s_nop 0
	s_nop 0
	s_nop 0
	s_nop 0
	s_nop 0
	s_nop 0
	s_nop 0
	s_nop 0
	s_nop 0
	s_nop 0
	s_nop 0
	s_nop 0
	s_nop 0
	s_nop 0
	s_nop 0
	s_nop 0
	s_nop 0
	s_nop 0
	s_nop 0
	s_nop 0
	s_nop 0
	s_nop 0
	s_nop 0
	s_nop 0
	s_nop 0
	s_nop 0
	s_nop 0
	s_nop 0
	s_nop 0
	s_nop 0
	s_nop 0
	s_nop 0
	s_nop 0
	s_nop 0
	s_nop 0
	s_nop 0
	s_nop 0
	s_nop 0
	s_nop 0
	s_nop 0
	s_nop 0
	s_nop 0
	s_nop 0
	s_nop 0
	s_nop 0
	s_nop 0
	s_nop 0
	s_nop 0
	s_nop 0
	s_nop 0
	s_nop 0
	s_nop 0
	s_nop 0
	s_nop 0
	s_nop 0
	s_nop 0
	s_nop 0
	s_nop 0
	s_nop 0
	s_nop 0
	s_nop 0
	s_nop 0
	s_nop 0
	s_nop 0
	s_nop 0
	s_nop 0
	s_nop 0
	s_nop 0
	s_nop 0
	s_nop 0
	s_nop 0
	s_nop 0
	s_nop 0
	s_nop 0
	s_nop 0
	s_nop 0
	s_nop 0
	s_nop 0
	s_nop 0
	s_nop 0
	s_nop 0
	s_nop 0
	s_nop 0
	s_nop 0
	s_nop 0
	s_nop 0
	s_nop 0
	s_nop 0
	s_nop 0
	s_nop 0
	s_nop 0
	s_nop 0
	s_nop 0
	s_nop 0
	s_nop 0
	s_nop 0
	s_nop 0
	s_nop 0
	s_nop 0
	s_nop 0
	s_nop 0
	s_nop 0
	s_nop 0
	s_nop 0
	s_nop 0
	s_nop 0
	s_nop 0
	s_nop 0
	s_nop 0
	s_nop 0
	s_nop 0
	s_nop 0
	s_nop 0
	s_nop 0
	s_nop 0
	s_nop 0
	s_nop 0
	s_nop 0
	s_nop 0
	s_nop 0
	s_nop 0
	s_nop 0
	s_nop 0
	s_nop 0
	s_nop 0
	s_nop 0
	s_nop 0
	s_nop 0
	s_nop 0
	s_nop 0
	s_nop 0
	s_nop 0
	s_nop 0
	s_nop 0
	s_nop 0
	s_nop 0
	s_nop 0
	s_nop 0
	s_nop 0
	s_nop 0
	s_nop 0
	s_nop 0
	s_nop 0
	s_nop 0
	s_nop 0
	s_nop 0
	s_nop 0
	s_nop 0
	s_nop 0
	s_nop 0
	s_nop 0
	s_nop 0
	s_nop 0
	s_nop 0
	s_nop 0
	s_nop 0
	s_nop 0
	s_nop 0
	s_nop 0
	s_nop 0
	s_nop 0
	s_nop 0
	s_nop 0
	s_nop 0
	s_nop 0
	s_nop 0
	s_nop 0
	s_nop 0
	s_nop 0
	s_nop 0
	s_nop 0
	s_nop 0
	s_nop 0
	s_nop 0
	s_nop 0
	s_nop 0
	s_nop 0
	s_nop 0
	s_nop 0
	s_nop 0
	s_nop 0
	s_nop 0
	s_nop 0
	s_nop 0
	s_nop 0
	s_nop 0
	s_nop 0
	s_nop 0
	s_nop 0
	s_nop 0
	s_nop 0
	s_nop 0
	s_nop 0
	s_nop 0
	s_nop 0
	s_nop 0
	s_nop 0
	s_nop 0
	s_nop 0
	s_nop 0
	s_nop 0
	s_nop 0
	s_nop 0
	s_nop 0
	s_nop 0
	s_nop 0
	s_nop 0
	s_nop 0
	s_nop 0
	s_nop 0
	s_nop 0
	s_nop 0
	s_nop 0
	s_nop 0
	s_nop 0
	s_nop 0
	s_nop 0
	s_nop 0
	s_nop 0
	s_nop 0
	s_nop 0
	s_nop 0
	s_nop 0
	s_nop 0
	s_nop 0
	s_nop 0
	s_nop 0
	s_nop 0
	s_nop 0
	s_nop 0
	s_nop 0
	s_nop 0
	s_nop 0
	s_nop 0
	s_nop 0
	s_nop 0
	s_nop 0
	s_nop 0
	s_nop 0
	s_nop 0
	s_nop 0
	s_nop 0
	s_nop 0
	s_nop 0
	s_nop 0
	s_nop 0
	s_nop 0
	s_nop 0
	s_nop 0
	s_nop 0
	s_nop 0
	s_nop 0
	s_nop 0
	s_nop 0
	s_nop 0
	s_nop 0
	s_nop 0
	s_nop 0
	s_nop 0
	s_nop 0
	s_nop 0
	s_nop 0
	s_nop 0
	s_nop 0
	s_nop 0
	s_nop 0
	s_nop 0
	s_nop 0
	s_nop 0
	s_nop 0
	s_nop 0
	s_nop 0
	s_nop 0
	s_nop 0
	s_nop 0
	s_nop 0
	s_nop 0
	s_nop 0
	s_nop 0
	s_nop 0
	s_nop 0
	s_nop 0
	s_nop 0
	s_nop 0
	s_nop 0
	s_nop 0
	s_nop 0
	s_nop 0
	s_nop 0
	s_nop 0
	s_nop 0
	s_nop 0
	s_nop 0
	s_nop 0
	s_nop 0
	s_nop 0
	s_nop 0
	s_nop 0
	s_nop 0
	s_nop 0
	s_nop 0
	s_nop 0
	s_nop 0
	s_nop 0
	s_nop 0
	s_nop 0
	s_nop 0
	s_nop 0
	s_nop 0
	s_nop 0
	s_nop 0
	s_nop 0
	s_nop 0
	s_nop 0
	s_nop 0
	s_nop 0
	s_nop 0
	s_nop 0
	s_nop 0
	s_nop 0
	s_nop 0
	s_nop 0
	s_nop 0
	s_nop 0
	s_nop 0
	s_nop 0
	s_nop 0
	s_nop 0
	s_nop 0
	s_nop 0
	s_nop 0
	s_nop 0
	s_nop 0
	s_nop 0
	s_nop 0
	s_nop 0
	s_nop 0
	s_nop 0
	s_nop 0
	s_nop 0
	s_nop 0
	s_nop 0
	s_nop 0
	s_nop 0
	s_nop 0
	s_nop 0
	s_nop 0
	s_nop 0
	s_nop 0
	s_nop 0
	s_nop 0
	s_nop 0
	s_nop 0
	s_nop 0
	s_nop 0
	s_nop 0
	s_nop 0
	s_nop 0
	s_nop 0
	s_nop 0
	s_nop 0
	s_nop 0
	s_nop 0
	s_nop 0
	s_nop 0
	s_nop 0
	s_nop 0
	s_nop 0
	s_nop 0
	s_nop 0
	s_nop 0
	s_nop 0
	s_nop 0
	s_nop 0
	s_nop 0
	s_nop 0
	s_nop 0
	s_nop 0
	s_nop 0
	s_nop 0
	s_nop 0
	s_nop 0
	s_nop 0
	s_nop 0
	s_nop 0
	s_nop 0
	s_nop 0
	s_nop 0
	s_nop 0
	s_nop 0
	s_nop 0
	s_nop 0
	s_nop 0
	s_nop 0
	s_nop 0
	s_nop 0
	s_nop 0
	s_nop 0
	s_nop 0
	s_nop 0
	s_nop 0
	s_nop 0
	s_nop 0
	s_nop 0
	s_nop 0
	s_nop 0
	s_nop 0
	s_nop 0
	s_nop 0
	s_nop 0
	s_nop 0
	s_nop 0
	s_nop 0
	s_nop 0
	s_nop 0
	s_nop 0
	s_nop 0
	s_nop 0
	s_nop 0
	s_nop 0
	s_nop 0
	s_nop 0
	s_nop 0
	s_nop 0
	s_nop 0
	s_nop 0
	s_nop 0
	s_nop 0
	s_nop 0
	s_nop 0
	s_nop 0
	s_nop 0
	s_nop 0
	s_nop 0
	s_nop 0
	s_nop 0
	s_nop 0
	s_nop 0
	s_nop 0
	s_nop 0
	s_nop 0
	s_nop 0
	s_nop 0
	s_nop 0
	s_nop 0
	s_nop 0
	s_nop 0
	s_nop 0
	s_nop 0
	s_nop 0
	s_nop 0
	s_nop 0
	s_nop 0
	s_nop 0
	s_nop 0
	s_nop 0
	s_nop 0
	s_nop 0
	s_nop 0
	s_nop 0
	s_nop 0
	s_nop 0
	s_nop 0
	s_nop 0
	s_nop 0
	s_nop 0
	s_nop 0
	s_nop 0
	s_nop 0
	s_nop 0
	s_nop 0
	s_nop 0
	s_nop 0
	s_nop 0
	s_nop 0
	s_nop 0
	s_nop 0
	s_nop 0
	s_nop 0
	s_nop 0
	s_nop 0
	s_nop 0
	s_nop 0
	s_nop 0
	s_nop 0
	s_nop 0
	s_nop 0
	s_nop 0
	s_nop 0
	s_nop 0
	s_nop 0
	s_nop 0
	s_nop 0
	s_nop 0
	s_nop 0
	s_nop 0
	s_nop 0
	s_nop 0
	s_nop 0
	s_nop 0
	s_nop 0
	s_nop 0
	s_nop 0
	s_nop 0
	s_nop 0
	s_nop 0
	s_nop 0
	s_nop 0
	s_nop 0
	s_nop 0
	s_nop 0
	s_nop 0
	s_nop 0
	s_nop 0
	s_nop 0
	s_nop 0
	s_nop 0
	s_nop 0
	s_nop 0
	s_nop 0
	s_nop 0
	s_nop 0
	s_nop 0
	s_nop 0
	s_nop 0
	s_nop 0
	s_nop 0
	s_nop 0
	s_nop 0
	s_nop 0
	s_nop 0
	s_nop 0
	s_nop 0
	s_nop 0
	s_nop 0
	s_nop 0
	s_nop 0
	s_nop 0
	s_nop 0
	s_nop 0
	s_nop 0
	s_nop 0
	s_nop 0
	s_nop 0
	s_nop 0
	s_nop 0
	s_nop 0
	s_nop 0
	s_nop 0
	s_nop 0
	s_nop 0
	s_nop 0
	s_nop 0
	s_nop 0
	s_nop 0
	s_nop 0
	s_nop 0
	s_nop 0
	s_nop 0
	s_nop 0
	s_nop 0
	s_nop 0
	s_nop 0
	s_nop 0
	s_nop 0
	s_nop 0
	s_nop 0
	s_nop 0
	s_nop 0
	s_nop 0
	s_nop 0
	s_nop 0
	s_nop 0
	s_nop 0
	s_nop 0
	s_nop 0
	s_nop 0
	s_nop 0
	s_nop 0
	s_nop 0
	s_nop 0
	s_nop 0
	s_nop 0
	s_nop 0
	s_nop 0
	s_nop 0
	s_nop 0
	s_nop 0
	s_nop 0
	s_nop 0
	s_nop 0
	s_nop 0
	s_nop 0
	s_nop 0
	s_nop 0
	s_nop 0
	s_nop 0
	s_nop 0
	s_nop 0
	s_nop 0
	s_nop 0
	s_nop 0
	s_nop 0
	s_nop 0
	s_nop 0
	s_nop 0
	s_nop 0
	s_nop 0
	s_nop 0
	s_nop 0
	s_nop 0
	s_nop 0
	s_nop 0
	s_nop 0
	s_nop 0
	s_nop 0
	s_nop 0
	s_nop 0
	s_nop 0
	s_nop 0
	s_nop 0
	s_nop 0
	s_nop 0
	s_nop 0
	s_nop 0
	s_nop 0
	s_nop 0
	s_nop 0
	s_nop 0
	s_nop 0
	s_nop 0
	s_nop 0
	s_nop 0
	s_nop 0
	s_nop 0
	s_nop 0
	s_nop 0
	s_nop 0
	s_nop 0
	s_nop 0
	s_nop 0
	s_nop 0
	s_nop 0
	s_nop 0
	s_nop 0
	s_nop 0
	s_nop 0
	s_nop 0
	s_nop 0
	s_nop 0
	s_nop 0
	s_nop 0
	s_nop 0
	s_nop 0
	s_nop 0
	s_nop 0
	s_nop 0
	s_nop 0
	s_nop 0
	s_nop 0
	s_nop 0
	s_nop 0
	s_nop 0
	s_nop 0
	s_nop 0
	s_nop 0
; __device__ __forceinline__ float frcp(float x) { return __builtin_amdgcn_rcpf(x); }
; __device__ __forceinline__ u32x4 pack8(f32x4 a, f32x4 b) { u32x4 w; w.x = pk_bf16(a[0], a[1]); w.y = pk_bf16(a[2], a[3]); w.z = pk_bf16(b[0], b[1]); w.w = pk_bf16(b[2], b[3]); return w; }
; __device__ __forceinline__ void unpack8(u32x4 w, float* f) { f[0] = bf_lo(w.x); f[1] = bf_hi(w.x); f[2] = bf_lo(w.y); f[3] = bf_hi(w.y); f[4] = bf_lo(w.z); f[5] = bf_hi(w.z); f[6] = bf_lo(w.w); f[7] = bf_hi(w.w); }
; #define E2_LOAD(buf, g) do { const bf16_t* gp_ = G + (size_t)(rowb + ((g) >> 2) * 128 + ((g) & 3) * 16) * GATEW + br * 1024 + colb; \
;         L[buf][0] = *(const u32x4*)gp_; L[buf][1] = *(const u32x4*)(gp_ + 1024); L[buf][2] = *(const u32x4*)(gp_ + 128); L[buf][3] = *(const u32x4*)(gp_ + 128 + 1024); } while (0)
;     __device__ __forceinline__ bool operator()(f32x4 (&acc)[2][2][4][2], const pg8::Unit& u, int wr, int wc, int fr, int fq) const {
;     ...
;         E2_LOAD(0, 0);
; #pragma unroll
;         for (int g = 0; g < 8; ++g) {
;             if (g < 7) E2_LOAD((g + 1) & 1, g + 1);
;             const int ai = g >> 2, m = g & 3, row = rowb + ai * 128 + m * 16;
; #pragma unroll
;             for (int bj = 0; bj < 2; ++bj) { const int col = colb + bj * 128; f32x4& v0 = acc[ai][bj][m][0]; f32x4& v1 = acc[ai][bj][m][1];
;                 float c[8], n[8]; unpack8(L[g & 1][2 * bj], c); unpack8(L[g & 1][2 * bj + 1], n); f32x4 o0, o1;
; #pragma unroll
;                 for (int j = 0; j < 8; ++j) { c[j] = fmaxf(c[j], 1e-30f); n[j] = last ? 1.0f : fmaxf(n[j], 1e-30f); }
; #pragma unroll
;                 for (int j = 0; j < 4; ++j) { v0[j] *= c[j] * frcp(n[j]); v1[j] *= c[4 + j] * frcp(n[4 + j]); }
; #pragma unroll
;                 for (int j = 0; j < 4; ++j) { o0[j] = v0[j] * n[j]; o1[j] = v1[j] * n[4 + j]; }
;                 *(u32x4*)(last ? MG + (size_t)row * DM + col : junk + (threadIdx.x & 511) * 8) = pack8(o0, o1); }
.Le2_last:
	v_ashrrev_i32_e32 v183, 31, v182
	v_lshlrev_b64 v[132:133], 11, v[182:183]
	v_lshl_add_u64 v[132:133], s[14:15], 0, v[132:133]
	v_lshl_add_u64 v[132:133], v[132:133], 0, v[180:181]
	global_load_dwordx4 v[134:137], v[130:131], off
	global_load_dwordx4 v[138:141], v[130:131], off offset:256
	v_lshl_add_u64 v[130:131], v[130:131], 0, s[58:59]
	global_load_dwordx4 v[142:145], v[130:131], off
	global_load_dwordx4 v[146:149], v[130:131], off offset:256
	v_lshl_add_u64 v[130:131], v[130:131], 0, s[58:59]
	global_load_dwordx4 v[150:153], v[130:131], off
	global_load_dwordx4 v[154:157], v[130:131], off offset:256
	v_lshl_add_u64 v[130:131], v[130:131], 0, s[58:59]
	global_load_dwordx4 v[158:161], v[130:131], off
	global_load_dwordx4 v[162:165], v[130:131], off offset:256
	v_lshl_add_u64 v[130:131], v[130:131], 0, s[54:55]
	global_load_dwordx4 v[220:223], v[130:131], off
	global_load_dwordx4 v[224:227], v[130:131], off offset:256
	v_lshl_add_u64 v[130:131], v[130:131], 0, s[58:59]
	global_load_dwordx4 v[228:231], v[130:131], off
	global_load_dwordx4 v[232:235], v[130:131], off offset:256
	v_lshl_add_u64 v[130:131], v[130:131], 0, s[58:59]
	global_load_dwordx4 v[242:245], v[130:131], off
	global_load_dwordx4 v[246:249], v[130:131], off offset:256
	v_lshl_add_u64 v[130:131], v[130:131], 0, s[58:59]
	global_load_dwordx4 v[210:213], v[130:131], off
	global_load_dwordx4 v[214:217], v[130:131], off offset:256
	s_mov_b32 s58, 0x8000
	s_mov_b32 s54, 0x28000
	s_waitcnt vmcnt(14)
	v_lshlrev_b32_e32 v184, 16, v134
	v_and_b32_e32 v185, s56, v134
	v_lshlrev_b32_e32 v186, 16, v135
	v_and_b32_e32 v187, s56, v135
	v_lshlrev_b32_e32 v188, 16, v136
	v_and_b32_e32 v189, s56, v136
	v_lshlrev_b32_e32 v218, 16, v137
	v_and_b32_e32 v219, s56, v137
	v_max_f32_e32 v184, s57, v184
	v_max_f32_e32 v185, s57, v185
	v_max_f32_e32 v186, s57, v186
	v_max_f32_e32 v187, s57, v187
	v_max_f32_e32 v188, s57, v188
	v_max_f32_e32 v189, s57, v189
	v_max_f32_e32 v218, s57, v218
	v_max_f32_e32 v219, s57, v219
	v_pk_mul_f32 v[126:127], v[126:127], v[184:185]
	v_pk_mul_f32 v[128:129], v[128:129], v[186:187]
	v_pk_mul_f32 v[122:123], v[122:123], v[188:189]
	v_pk_mul_f32 v[124:125], v[124:125], v[218:219]
	v_cvt_pk_bf16_f32 v134, v126, v127
	v_cvt_pk_bf16_f32 v135, v128, v129
	v_cvt_pk_bf16_f32 v136, v122, v123
	v_cvt_pk_bf16_f32 v137, v124, v125
	global_store_dwordx4 v[132:133], v[134:137], off
	v_lshlrev_b32_e32 v184, 16, v138
	v_and_b32_e32 v185, s56, v138
	v_lshlrev_b32_e32 v186, 16, v139
	v_and_b32_e32 v187, s56, v139
	v_lshlrev_b32_e32 v188, 16, v140
	v_and_b32_e32 v189, s56, v140
	v_lshlrev_b32_e32 v218, 16, v141
	v_and_b32_e32 v219, s56, v141
	v_max_f32_e32 v184, s57, v184
	v_max_f32_e32 v185, s57, v185
	v_max_f32_e32 v186, s57, v186
	v_max_f32_e32 v187, s57, v187
	v_max_f32_e32 v188, s57, v188
	v_max_f32_e32 v189, s57, v189
	v_max_f32_e32 v218, s57, v218
	v_max_f32_e32 v219, s57, v219
	v_pk_mul_f32 v[94:95], v[94:95], v[184:185]
	v_pk_mul_f32 v[96:97], v[96:97], v[186:187]
	v_pk_mul_f32 v[90:91], v[90:91], v[188:189]
	v_pk_mul_f32 v[92:93], v[92:93], v[218:219]
	v_cvt_pk_bf16_f32 v138, v94, v95
	v_cvt_pk_bf16_f32 v139, v96, v97
	v_cvt_pk_bf16_f32 v140, v90, v91
	v_cvt_pk_bf16_f32 v141, v92, v93
	global_store_dwordx4 v[132:133], v[138:141], off offset:256
	v_lshl_add_u64 v[132:133], v[132:133], 0, s[58:59]
	s_waitcnt vmcnt(14)
	v_lshlrev_b32_e32 v184, 16, v142
	v_and_b32_e32 v185, s56, v142
	v_lshlrev_b32_e32 v186, 16, v143
	v_and_b32_e32 v187, s56, v143
	v_lshlrev_b32_e32 v188, 16, v144
	v_and_b32_e32 v189, s56, v144
	v_lshlrev_b32_e32 v218, 16, v145
	v_and_b32_e32 v219, s56, v145
	v_max_f32_e32 v184, s57, v184
	v_max_f32_e32 v185, s57, v185
	v_max_f32_e32 v186, s57, v186
	v_max_f32_e32 v187, s57, v187
	v_max_f32_e32 v188, s57, v188
	v_max_f32_e32 v189, s57, v189
	v_max_f32_e32 v218, s57, v218
	v_max_f32_e32 v219, s57, v219
	v_pk_mul_f32 v[118:119], v[118:119], v[184:185]
	v_pk_mul_f32 v[120:121], v[120:121], v[186:187]
	v_pk_mul_f32 v[114:115], v[114:115], v[188:189]
	v_pk_mul_f32 v[116:117], v[116:117], v[218:219]
	v_cvt_pk_bf16_f32 v142, v118, v119
	v_cvt_pk_bf16_f32 v143, v120, v121
	v_cvt_pk_bf16_f32 v144, v114, v115
	v_cvt_pk_bf16_f32 v145, v116, v117
	global_store_dwordx4 v[132:133], v[142:145], off
	v_lshlrev_b32_e32 v184, 16, v146
	v_and_b32_e32 v185, s56, v146
	v_lshlrev_b32_e32 v186, 16, v147
	v_and_b32_e32 v187, s56, v147
	v_lshlrev_b32_e32 v188, 16, v148
	v_and_b32_e32 v189, s56, v148
	v_lshlrev_b32_e32 v218, 16, v149
	v_and_b32_e32 v219, s56, v149
	v_max_f32_e32 v184, s57, v184
	v_max_f32_e32 v185, s57, v185
	v_max_f32_e32 v186, s57, v186
	v_max_f32_e32 v187, s57, v187
	v_max_f32_e32 v188, s57, v188
	v_max_f32_e32 v189, s57, v189
	v_max_f32_e32 v218, s57, v218
	v_max_f32_e32 v219, s57, v219
	v_pk_mul_f32 v[86:87], v[86:87], v[184:185]
	v_pk_mul_f32 v[88:89], v[88:89], v[186:187]
	v_pk_mul_f32 v[82:83], v[82:83], v[188:189]
	v_pk_mul_f32 v[84:85], v[84:85], v[218:219]
	v_cvt_pk_bf16_f32 v146, v86, v87
	v_cvt_pk_bf16_f32 v147, v88, v89
	v_cvt_pk_bf16_f32 v148, v82, v83
	v_cvt_pk_bf16_f32 v149, v84, v85
	global_store_dwordx4 v[132:133], v[146:149], off offset:256
	v_lshl_add_u64 v[132:133], v[132:133], 0, s[58:59]
	s_waitcnt vmcnt(14)
; __device__ __forceinline__ float frcp(float x) { return __builtin_amdgcn_rcpf(x); }
; __device__ __forceinline__ u32x4 pack8(f32x4 a, f32x4 b) { u32x4 w; w.x = pk_bf16(a[0], a[1]); w.y = pk_bf16(a[2], a[3]); w.z = pk_bf16(b[0], b[1]); w.w = pk_bf16(b[2], b[3]); return w; }
; __device__ __forceinline__ void unpack8(u32x4 w, float* f) { f[0] = bf_lo(w.x); f[1] = bf_hi(w.x); f[2] = bf_lo(w.y); f[3] = bf_hi(w.y); f[4] = bf_lo(w.z); f[5] = bf_hi(w.z); f[6] = bf_lo(w.w); f[7] = bf_hi(w.w); }
; #define E2_LOAD(buf, g) do { const bf16_t* gp_ = G + (size_t)(rowb + ((g) >> 2) * 128 + ((g) & 3) * 16) * GATEW + br * 1024 + colb; \
;         L[buf][0] = *(const u32x4*)gp_; L[buf][1] = *(const u32x4*)(gp_ + 1024); L[buf][2] = *(const u32x4*)(gp_ + 128); L[buf][3] = *(const u32x4*)(gp_ + 128 + 1024); } while (0)
;     __device__ __forceinline__ bool operator()(f32x4 (&acc)[2][2][4][2], const pg8::Unit& u, int wr, int wc, int fr, int fq) const {
;     ...
;         E2_LOAD(0, 0);
; #pragma unroll
;         for (int g = 0; g < 8; ++g) {
;             if (g < 7) E2_LOAD((g + 1) & 1, g + 1);
;             const int ai = g >> 2, m = g & 3, row = rowb + ai * 128 + m * 16;
; #pragma unroll
;             for (int bj = 0; bj < 2; ++bj) { const int col = colb + bj * 128; f32x4& v0 = acc[ai][bj][m][0]; f32x4& v1 = acc[ai][bj][m][1];
;                 float c[8], n[8]; unpack8(L[g & 1][2 * bj], c); unpack8(L[g & 1][2 * bj + 1], n); f32x4 o0, o1;
; #pragma unroll
;                 for (int j = 0; j < 8; ++j) { c[j] = fmaxf(c[j], 1e-30f); n[j] = last ? 1.0f : fmaxf(n[j], 1e-30f); }
; #pragma unroll
;                 for (int j = 0; j < 4; ++j) { v0[j] *= c[j] * frcp(n[j]); v1[j] *= c[4 + j] * frcp(n[4 + j]); }
; #pragma unroll
;                 for (int j = 0; j < 4; ++j) { o0[j] = v0[j] * n[j]; o1[j] = v1[j] * n[4 + j]; }
;                 *(u32x4*)(last ? MG + (size_t)row * DM + col : junk + (threadIdx.x & 511) * 8) = pack8(o0, o1); }
	v_lshlrev_b32_e32 v184, 16, v150
	v_and_b32_e32 v185, s56, v150
	v_lshlrev_b32_e32 v186, 16, v151
	v_and_b32_e32 v187, s56, v151
	v_lshlrev_b32_e32 v188, 16, v152
	v_and_b32_e32 v189, s56, v152
	v_lshlrev_b32_e32 v218, 16, v153
	v_and_b32_e32 v219, s56, v153
	v_max_f32_e32 v184, s57, v184
	v_max_f32_e32 v185, s57, v185
	v_max_f32_e32 v186, s57, v186
	v_max_f32_e32 v187, s57, v187
	v_max_f32_e32 v188, s57, v188
	v_max_f32_e32 v189, s57, v189
	v_max_f32_e32 v218, s57, v218
	v_max_f32_e32 v219, s57, v219
	v_pk_mul_f32 v[110:111], v[110:111], v[184:185]
	v_pk_mul_f32 v[112:113], v[112:113], v[186:187]
	v_pk_mul_f32 v[106:107], v[106:107], v[188:189]
	v_pk_mul_f32 v[108:109], v[108:109], v[218:219]
	v_cvt_pk_bf16_f32 v150, v110, v111
	v_cvt_pk_bf16_f32 v151, v112, v113
	v_cvt_pk_bf16_f32 v152, v106, v107
	v_cvt_pk_bf16_f32 v153, v108, v109
	global_store_dwordx4 v[132:133], v[150:153], off
	v_lshlrev_b32_e32 v184, 16, v154
	v_and_b32_e32 v185, s56, v154
	v_lshlrev_b32_e32 v186, 16, v155
	v_and_b32_e32 v187, s56, v155
	v_lshlrev_b32_e32 v188, 16, v156
	v_and_b32_e32 v189, s56, v156
	v_lshlrev_b32_e32 v218, 16, v157
	v_and_b32_e32 v219, s56, v157
	v_max_f32_e32 v184, s57, v184
	v_max_f32_e32 v185, s57, v185
	v_max_f32_e32 v186, s57, v186
	v_max_f32_e32 v187, s57, v187
	v_max_f32_e32 v188, s57, v188
	v_max_f32_e32 v189, s57, v189
	v_max_f32_e32 v218, s57, v218
	v_max_f32_e32 v219, s57, v219
	v_pk_mul_f32 v[78:79], v[78:79], v[184:185]
	v_pk_mul_f32 v[80:81], v[80:81], v[186:187]
	v_pk_mul_f32 v[74:75], v[74:75], v[188:189]
	v_pk_mul_f32 v[76:77], v[76:77], v[218:219]
	v_cvt_pk_bf16_f32 v154, v78, v79
	v_cvt_pk_bf16_f32 v155, v80, v81
	v_cvt_pk_bf16_f32 v156, v74, v75
	v_cvt_pk_bf16_f32 v157, v76, v77
	global_store_dwordx4 v[132:133], v[154:157], off offset:256
	v_lshl_add_u64 v[132:133], v[132:133], 0, s[58:59]
	s_waitcnt vmcnt(14)
	v_lshlrev_b32_e32 v184, 16, v158
	v_and_b32_e32 v185, s56, v158
	v_lshlrev_b32_e32 v186, 16, v159
	v_and_b32_e32 v187, s56, v159
	v_lshlrev_b32_e32 v188, 16, v160
	v_and_b32_e32 v189, s56, v160
	v_lshlrev_b32_e32 v218, 16, v161
	v_and_b32_e32 v219, s56, v161
	v_max_f32_e32 v184, s57, v184
	v_max_f32_e32 v185, s57, v185
	v_max_f32_e32 v186, s57, v186
	v_max_f32_e32 v187, s57, v187
	v_max_f32_e32 v188, s57, v188
	v_max_f32_e32 v189, s57, v189
	v_max_f32_e32 v218, s57, v218
	v_max_f32_e32 v219, s57, v219
	v_pk_mul_f32 v[102:103], v[102:103], v[184:185]
	v_pk_mul_f32 v[104:105], v[104:105], v[186:187]
	v_pk_mul_f32 v[98:99], v[98:99], v[188:189]
	v_pk_mul_f32 v[100:101], v[100:101], v[218:219]
	v_cvt_pk_bf16_f32 v158, v102, v103
	v_cvt_pk_bf16_f32 v159, v104, v105
	v_cvt_pk_bf16_f32 v160, v98, v99
	v_cvt_pk_bf16_f32 v161, v100, v101
	global_store_dwordx4 v[132:133], v[158:161], off
	v_lshlrev_b32_e32 v184, 16, v162
	v_and_b32_e32 v185, s56, v162
	v_lshlrev_b32_e32 v186, 16, v163
	v_and_b32_e32 v187, s56, v163
	v_lshlrev_b32_e32 v188, 16, v164
	v_and_b32_e32 v189, s56, v164
	v_lshlrev_b32_e32 v218, 16, v165
	v_and_b32_e32 v219, s56, v165
	v_max_f32_e32 v184, s57, v184
	v_max_f32_e32 v185, s57, v185
	v_max_f32_e32 v186, s57, v186
	v_max_f32_e32 v187, s57, v187
	v_max_f32_e32 v188, s57, v188
	v_max_f32_e32 v189, s57, v189
	v_max_f32_e32 v218, s57, v218
	v_max_f32_e32 v219, s57, v219
	v_pk_mul_f32 v[70:71], v[70:71], v[184:185]
	v_pk_mul_f32 v[72:73], v[72:73], v[186:187]
	v_pk_mul_f32 v[66:67], v[66:67], v[188:189]
	v_pk_mul_f32 v[68:69], v[68:69], v[218:219]
	v_cvt_pk_bf16_f32 v162, v70, v71
	v_cvt_pk_bf16_f32 v163, v72, v73
	v_cvt_pk_bf16_f32 v164, v66, v67
	v_cvt_pk_bf16_f32 v165, v68, v69
	global_store_dwordx4 v[132:133], v[162:165], off offset:256
	v_lshl_add_u64 v[132:133], v[132:133], 0, s[54:55]
	s_waitcnt vmcnt(14)
	v_lshlrev_b32_e32 v184, 16, v220
	v_and_b32_e32 v185, s56, v220
	v_lshlrev_b32_e32 v186, 16, v221
	v_and_b32_e32 v187, s56, v221
	v_lshlrev_b32_e32 v188, 16, v222
	v_and_b32_e32 v189, s56, v222
	v_lshlrev_b32_e32 v218, 16, v223
	v_and_b32_e32 v219, s56, v223
	v_max_f32_e32 v184, s57, v184
	v_max_f32_e32 v185, s57, v185
	v_max_f32_e32 v186, s57, v186
	v_max_f32_e32 v187, s57, v187
	v_max_f32_e32 v188, s57, v188
	v_max_f32_e32 v189, s57, v189
	v_max_f32_e32 v218, s57, v218
	v_max_f32_e32 v219, s57, v219
	v_pk_mul_f32 v[62:63], v[62:63], v[184:185]
	v_pk_mul_f32 v[64:65], v[64:65], v[186:187]
	v_pk_mul_f32 v[58:59], v[58:59], v[188:189]
	v_pk_mul_f32 v[60:61], v[60:61], v[218:219]
	v_cvt_pk_bf16_f32 v220, v62, v63
	v_cvt_pk_bf16_f32 v221, v64, v65
	v_cvt_pk_bf16_f32 v222, v58, v59
	v_cvt_pk_bf16_f32 v223, v60, v61
	global_store_dwordx4 v[132:133], v[220:223], off
	v_lshlrev_b32_e32 v184, 16, v224
	v_and_b32_e32 v185, s56, v224
	v_lshlrev_b32_e32 v186, 16, v225
	v_and_b32_e32 v187, s56, v225
	v_lshlrev_b32_e32 v188, 16, v226
	v_and_b32_e32 v189, s56, v226
	v_lshlrev_b32_e32 v218, 16, v227
	v_and_b32_e32 v219, s56, v227
	v_max_f32_e32 v184, s57, v184
	v_max_f32_e32 v185, s57, v185
	v_max_f32_e32 v186, s57, v186
	v_max_f32_e32 v187, s57, v187
	v_max_f32_e32 v188, s57, v188
	v_max_f32_e32 v189, s57, v189
	v_max_f32_e32 v218, s57, v218
	v_max_f32_e32 v219, s57, v219
	v_pk_mul_f32 v[30:31], v[30:31], v[184:185]
	v_pk_mul_f32 v[32:33], v[32:33], v[186:187]
	v_pk_mul_f32 v[26:27], v[26:27], v[188:189]
	v_pk_mul_f32 v[28:29], v[28:29], v[218:219]
	v_cvt_pk_bf16_f32 v224, v30, v31
	v_cvt_pk_bf16_f32 v225, v32, v33
	v_cvt_pk_bf16_f32 v226, v26, v27
	v_cvt_pk_bf16_f32 v227, v28, v29
	global_store_dwordx4 v[132:133], v[224:227], off offset:256
	v_lshl_add_u64 v[132:133], v[132:133], 0, s[58:59]
	s_waitcnt vmcnt(14)
; __device__ __forceinline__ float frcp(float x) { return __builtin_amdgcn_rcpf(x); }
; __device__ __forceinline__ u32x4 pack8(f32x4 a, f32x4 b) { u32x4 w; w.x = pk_bf16(a[0], a[1]); w.y = pk_bf16(a[2], a[3]); w.z = pk_bf16(b[0], b[1]); w.w = pk_bf16(b[2], b[3]); return w; }
; __device__ __forceinline__ void unpack8(u32x4 w, float* f) { f[0] = bf_lo(w.x); f[1] = bf_hi(w.x); f[2] = bf_lo(w.y); f[3] = bf_hi(w.y); f[4] = bf_lo(w.z); f[5] = bf_hi(w.z); f[6] = bf_lo(w.w); f[7] = bf_hi(w.w); }
; #define E2_LOAD(buf, g) do { const bf16_t* gp_ = G + (size_t)(rowb + ((g) >> 2) * 128 + ((g) & 3) * 16) * GATEW + br * 1024 + colb; \
;         L[buf][0] = *(const u32x4*)gp_; L[buf][1] = *(const u32x4*)(gp_ + 1024); L[buf][2] = *(const u32x4*)(gp_ + 128); L[buf][3] = *(const u32x4*)(gp_ + 128 + 1024); } while (0)
;     __device__ __forceinline__ bool operator()(f32x4 (&acc)[2][2][4][2], const pg8::Unit& u, int wr, int wc, int fr, int fq) const {
;     ...
;         E2_LOAD(0, 0);
; #pragma unroll
;         for (int g = 0; g < 8; ++g) {
;             if (g < 7) E2_LOAD((g + 1) & 1, g + 1);
;             const int ai = g >> 2, m = g & 3, row = rowb + ai * 128 + m * 16;
; #pragma unroll
;             for (int bj = 0; bj < 2; ++bj) { const int col = colb + bj * 128; f32x4& v0 = acc[ai][bj][m][0]; f32x4& v1 = acc[ai][bj][m][1];
;                 float c[8], n[8]; unpack8(L[g & 1][2 * bj], c); unpack8(L[g & 1][2 * bj + 1], n); f32x4 o0, o1;
; #pragma unroll
;                 for (int j = 0; j < 8; ++j) { c[j] = fmaxf(c[j], 1e-30f); n[j] = last ? 1.0f : fmaxf(n[j], 1e-30f); }
; #pragma unroll
;                 for (int j = 0; j < 4; ++j) { v0[j] *= c[j] * frcp(n[j]); v1[j] *= c[4 + j] * frcp(n[4 + j]); }
; #pragma unroll
;                 for (int j = 0; j < 4; ++j) { o0[j] = v0[j] * n[j]; o1[j] = v1[j] * n[4 + j]; }
;                 *(u32x4*)(last ? MG + (size_t)row * DM + col : junk + (threadIdx.x & 511) * 8) = pack8(o0, o1); }
	v_lshlrev_b32_e32 v184, 16, v228
	v_and_b32_e32 v185, s56, v228
	v_lshlrev_b32_e32 v186, 16, v229
	v_and_b32_e32 v187, s56, v229
	v_lshlrev_b32_e32 v188, 16, v230
	v_and_b32_e32 v189, s56, v230
	v_lshlrev_b32_e32 v218, 16, v231
	v_and_b32_e32 v219, s56, v231
	v_max_f32_e32 v184, s57, v184
	v_max_f32_e32 v185, s57, v185
	v_max_f32_e32 v186, s57, v186
	v_max_f32_e32 v187, s57, v187
	v_max_f32_e32 v188, s57, v188
	v_max_f32_e32 v189, s57, v189
	v_max_f32_e32 v218, s57, v218
	v_max_f32_e32 v219, s57, v219
	v_pk_mul_f32 v[54:55], v[54:55], v[184:185]
	v_pk_mul_f32 v[56:57], v[56:57], v[186:187]
	v_pk_mul_f32 v[50:51], v[50:51], v[188:189]
	v_pk_mul_f32 v[52:53], v[52:53], v[218:219]
	v_cvt_pk_bf16_f32 v228, v54, v55
	v_cvt_pk_bf16_f32 v229, v56, v57
	v_cvt_pk_bf16_f32 v230, v50, v51
	v_cvt_pk_bf16_f32 v231, v52, v53
	global_store_dwordx4 v[132:133], v[228:231], off
	v_lshlrev_b32_e32 v184, 16, v232
	v_and_b32_e32 v185, s56, v232
	v_lshlrev_b32_e32 v186, 16, v233
	v_and_b32_e32 v187, s56, v233
	v_lshlrev_b32_e32 v188, 16, v234
	v_and_b32_e32 v189, s56, v234
	v_lshlrev_b32_e32 v218, 16, v235
	v_and_b32_e32 v219, s56, v235
	v_max_f32_e32 v184, s57, v184
	v_max_f32_e32 v185, s57, v185
	v_max_f32_e32 v186, s57, v186
	v_max_f32_e32 v187, s57, v187
	v_max_f32_e32 v188, s57, v188
	v_max_f32_e32 v189, s57, v189
	v_max_f32_e32 v218, s57, v218
	v_max_f32_e32 v219, s57, v219
	v_pk_mul_f32 v[22:23], v[22:23], v[184:185]
	v_pk_mul_f32 v[24:25], v[24:25], v[186:187]
	v_pk_mul_f32 v[18:19], v[18:19], v[188:189]
	v_pk_mul_f32 v[20:21], v[20:21], v[218:219]
	v_cvt_pk_bf16_f32 v232, v22, v23
	v_cvt_pk_bf16_f32 v233, v24, v25
	v_cvt_pk_bf16_f32 v234, v18, v19
	v_cvt_pk_bf16_f32 v235, v20, v21
	global_store_dwordx4 v[132:133], v[232:235], off offset:256
	v_lshl_add_u64 v[132:133], v[132:133], 0, s[58:59]
	s_waitcnt vmcnt(14)
	v_lshlrev_b32_e32 v184, 16, v242
	v_and_b32_e32 v185, s56, v242
	v_lshlrev_b32_e32 v186, 16, v243
	v_and_b32_e32 v187, s56, v243
	v_lshlrev_b32_e32 v188, 16, v244
	v_and_b32_e32 v189, s56, v244
	v_lshlrev_b32_e32 v218, 16, v245
	v_and_b32_e32 v219, s56, v245
	v_max_f32_e32 v184, s57, v184
	v_max_f32_e32 v185, s57, v185
	v_max_f32_e32 v186, s57, v186
	v_max_f32_e32 v187, s57, v187
	v_max_f32_e32 v188, s57, v188
	v_max_f32_e32 v189, s57, v189
	v_max_f32_e32 v218, s57, v218
	v_max_f32_e32 v219, s57, v219
	v_pk_mul_f32 v[46:47], v[46:47], v[184:185]
	v_pk_mul_f32 v[48:49], v[48:49], v[186:187]
	v_pk_mul_f32 v[42:43], v[42:43], v[188:189]
	v_pk_mul_f32 v[44:45], v[44:45], v[218:219]
	v_cvt_pk_bf16_f32 v242, v46, v47
	v_cvt_pk_bf16_f32 v243, v48, v49
	v_cvt_pk_bf16_f32 v244, v42, v43
	v_cvt_pk_bf16_f32 v245, v44, v45
	global_store_dwordx4 v[132:133], v[242:245], off
	v_lshlrev_b32_e32 v184, 16, v246
	v_and_b32_e32 v185, s56, v246
	v_lshlrev_b32_e32 v186, 16, v247
	v_and_b32_e32 v187, s56, v247
	v_lshlrev_b32_e32 v188, 16, v248
	v_and_b32_e32 v189, s56, v248
	v_lshlrev_b32_e32 v218, 16, v249
	v_and_b32_e32 v219, s56, v249
	v_max_f32_e32 v184, s57, v184
	v_max_f32_e32 v185, s57, v185
	v_max_f32_e32 v186, s57, v186
	v_max_f32_e32 v187, s57, v187
	v_max_f32_e32 v188, s57, v188
	v_max_f32_e32 v189, s57, v189
	v_max_f32_e32 v218, s57, v218
	v_max_f32_e32 v219, s57, v219
	v_pk_mul_f32 v[14:15], v[14:15], v[184:185]
	v_pk_mul_f32 v[16:17], v[16:17], v[186:187]
	v_pk_mul_f32 v[10:11], v[10:11], v[188:189]
	v_pk_mul_f32 v[12:13], v[12:13], v[218:219]
	v_cvt_pk_bf16_f32 v246, v14, v15
	v_cvt_pk_bf16_f32 v247, v16, v17
	v_cvt_pk_bf16_f32 v248, v10, v11
	v_cvt_pk_bf16_f32 v249, v12, v13
	global_store_dwordx4 v[132:133], v[246:249], off offset:256
	v_lshl_add_u64 v[132:133], v[132:133], 0, s[58:59]
	s_waitcnt vmcnt(14)
	v_lshlrev_b32_e32 v184, 16, v210
	v_and_b32_e32 v185, s56, v210
	v_lshlrev_b32_e32 v186, 16, v211
	v_and_b32_e32 v187, s56, v211
	v_lshlrev_b32_e32 v188, 16, v212
	v_and_b32_e32 v189, s56, v212
	v_lshlrev_b32_e32 v218, 16, v213
	v_and_b32_e32 v219, s56, v213
	v_max_f32_e32 v184, s57, v184
	v_max_f32_e32 v185, s57, v185
	v_max_f32_e32 v186, s57, v186
	v_max_f32_e32 v187, s57, v187
	v_max_f32_e32 v188, s57, v188
	v_max_f32_e32 v189, s57, v189
	v_max_f32_e32 v218, s57, v218
	v_max_f32_e32 v219, s57, v219
	v_pk_mul_f32 v[38:39], v[38:39], v[184:185]
	v_pk_mul_f32 v[40:41], v[40:41], v[186:187]
	v_pk_mul_f32 v[34:35], v[34:35], v[188:189]
	v_pk_mul_f32 v[36:37], v[36:37], v[218:219]
	v_cvt_pk_bf16_f32 v210, v38, v39
	v_cvt_pk_bf16_f32 v211, v40, v41
	v_cvt_pk_bf16_f32 v212, v34, v35
	v_cvt_pk_bf16_f32 v213, v36, v37
	global_store_dwordx4 v[132:133], v[210:213], off
	v_lshlrev_b32_e32 v184, 16, v214
	v_and_b32_e32 v185, s56, v214
	v_lshlrev_b32_e32 v186, 16, v215
	v_and_b32_e32 v187, s56, v215
	v_lshlrev_b32_e32 v188, 16, v216
	v_and_b32_e32 v189, s56, v216
	v_lshlrev_b32_e32 v218, 16, v217
	v_and_b32_e32 v219, s56, v217
	v_max_f32_e32 v184, s57, v184
	v_max_f32_e32 v185, s57, v185
	v_max_f32_e32 v186, s57, v186
	v_max_f32_e32 v187, s57, v187
	v_max_f32_e32 v188, s57, v188
	v_max_f32_e32 v189, s57, v189
	v_max_f32_e32 v218, s57, v218
	v_max_f32_e32 v219, s57, v219
	v_pk_mul_f32 v[6:7], v[6:7], v[184:185]
	v_pk_mul_f32 v[8:9], v[8:9], v[186:187]
	v_pk_mul_f32 v[2:3], v[2:3], v[188:189]
	v_pk_mul_f32 v[4:5], v[4:5], v[218:219]
	v_cvt_pk_bf16_f32 v214, v6, v7
	v_cvt_pk_bf16_f32 v215, v8, v9
	v_cvt_pk_bf16_f32 v216, v2, v3
	v_cvt_pk_bf16_f32 v217, v4, v5
	global_store_dwordx4 v[132:133], v[214:217], off offset:256
; #define PG8_BAR __builtin_amdgcn_s_barrier()
; #define PG8_ZERO() do { _Pragma("unroll") for (int a = 0; a < 2; ++a) _Pragma("unroll") for (int b = 0; b < 2; ++b) _Pragma("unroll") for (int m = 0; m < 4; ++m) _Pragma("unroll") for (int n = 0; n < 2; ++n) acc[a][b][m][n] = (f32x4){0.f, 0.f, 0.f, 0.f}; } while (0)
; template <class Epi, class Sched>
; __device__ __forceinline__ void gemm_phase(LAS unsigned char* lds, const int K, const Sched& S, const Epi& E) {
;     ...
;         if (wr == 0) PG8_BAR;
;         bool zero = true;
;         if constexpr (!Epi::AFTER_DRAIN) zero = E(acc, cur, wr, wc, fr, fq);
;         if (!has_next) break;
;         if (Epi::ZERO_AFTER || zero) PG8_ZERO();
;         cur = nxt; cA = nA; cB = nB; ++ui;
;         if (wr == 1) PG8_BAR;
.Le2_done:
	s_andn2_b64 vcc, exec, s[52:53]
	s_mov_b64 s[52:53], -1
	v_readlane_b32 s58, v252, 9
	v_readlane_b32 s59, v252, 10
	s_cbranch_vccnz .LBB0_743
	s_andn2_b64 vcc, exec, s[6:7]
	s_cbranch_vccnz .LBB0_765
	v_mov_b32_e32 v2, 0
	v_mov_b32_e32 v3, v2
	v_mov_b32_e32 v4, v2
	v_mov_b32_e32 v5, v2
	v_mov_b32_e32 v6, v2
	v_mov_b32_e32 v7, v2
	v_mov_b32_e32 v8, v2
	v_mov_b32_e32 v9, v2
	v_mov_b32_e32 v10, v2
	v_mov_b32_e32 v11, v2
	v_mov_b32_e32 v12, v2
	v_mov_b32_e32 v13, v2
	v_mov_b32_e32 v14, v2
	v_mov_b32_e32 v15, v2
	v_mov_b32_e32 v16, v2
	v_mov_b32_e32 v17, v2
	v_mov_b32_e32 v18, v2
	v_mov_b32_e32 v19, v2
	v_mov_b32_e32 v20, v2
	v_mov_b32_e32 v21, v2
	v_mov_b32_e32 v22, v2
	v_mov_b32_e32 v23, v2
	v_mov_b32_e32 v24, v2
	v_mov_b32_e32 v25, v2
	v_mov_b32_e32 v26, v2
	v_mov_b32_e32 v27, v2
	v_mov_b32_e32 v28, v2
	v_mov_b32_e32 v29, v2
	v_mov_b32_e32 v30, v2
	v_mov_b32_e32 v31, v2
	v_mov_b32_e32 v32, v2
	v_mov_b32_e32 v33, v2
	v_mov_b32_e32 v34, v2
	v_mov_b32_e32 v35, v2
	v_mov_b32_e32 v36, v2
	v_mov_b32_e32 v37, v2
	v_mov_b32_e32 v38, v2
	v_mov_b32_e32 v39, v2
	v_mov_b32_e32 v40, v2
	v_mov_b32_e32 v41, v2
	v_mov_b32_e32 v42, v2
	v_mov_b32_e32 v43, v2
	v_mov_b32_e32 v44, v2
	v_mov_b32_e32 v45, v2
	v_mov_b32_e32 v46, v2
	v_mov_b32_e32 v47, v2
	v_mov_b32_e32 v48, v2
	v_mov_b32_e32 v49, v2
	v_mov_b32_e32 v50, v2
	v_mov_b32_e32 v51, v2
	v_mov_b32_e32 v52, v2
	v_mov_b32_e32 v53, v2
	v_mov_b32_e32 v54, v2
	v_mov_b32_e32 v55, v2
	v_mov_b32_e32 v56, v2
	v_mov_b32_e32 v57, v2
	v_mov_b32_e32 v58, v2
	v_mov_b32_e32 v59, v2
	v_mov_b32_e32 v60, v2
	v_mov_b32_e32 v61, v2
	v_mov_b32_e32 v62, v2
	v_mov_b32_e32 v63, v2
	v_mov_b32_e32 v64, v2
	v_mov_b32_e32 v65, v2
	v_mov_b32_e32 v66, v2
	v_mov_b32_e32 v67, v2
	v_mov_b32_e32 v68, v2
	v_mov_b32_e32 v69, v2
	v_mov_b32_e32 v70, v2
	v_mov_b32_e32 v71, v2
	v_mov_b32_e32 v72, v2
	v_mov_b32_e32 v73, v2
	v_mov_b32_e32 v74, v2
	v_mov_b32_e32 v75, v2
	v_mov_b32_e32 v76, v2
	v_mov_b32_e32 v77, v2
	v_mov_b32_e32 v78, v2
	v_mov_b32_e32 v79, v2
	v_mov_b32_e32 v80, v2
	v_mov_b32_e32 v81, v2
	v_mov_b32_e32 v82, v2
	v_mov_b32_e32 v83, v2
	v_mov_b32_e32 v84, v2
	v_mov_b32_e32 v85, v2
	v_mov_b32_e32 v86, v2
	v_mov_b32_e32 v87, v2
	v_mov_b32_e32 v88, v2
	v_mov_b32_e32 v89, v2
	v_mov_b32_e32 v90, v2
	v_mov_b32_e32 v91, v2
	v_mov_b32_e32 v92, v2
	v_mov_b32_e32 v93, v2
	v_mov_b32_e32 v94, v2
	v_mov_b32_e32 v95, v2
	v_mov_b32_e32 v96, v2
	v_mov_b32_e32 v97, v2
	v_mov_b32_e32 v98, v2
	v_mov_b32_e32 v99, v2
	v_mov_b32_e32 v100, v2
	v_mov_b32_e32 v101, v2
	v_mov_b32_e32 v102, v2
	v_mov_b32_e32 v103, v2
	v_mov_b32_e32 v104, v2
	v_mov_b32_e32 v105, v2
	v_mov_b32_e32 v106, v2
	v_mov_b32_e32 v107, v2
	v_mov_b32_e32 v108, v2
	v_mov_b32_e32 v109, v2
	v_mov_b32_e32 v110, v2
	v_mov_b32_e32 v111, v2
	v_mov_b32_e32 v112, v2
	v_mov_b32_e32 v113, v2
	v_mov_b32_e32 v114, v2
	v_mov_b32_e32 v115, v2
	v_mov_b32_e32 v116, v2
	v_mov_b32_e32 v117, v2
	v_mov_b32_e32 v118, v2
	v_mov_b32_e32 v119, v2
	v_mov_b32_e32 v120, v2
	v_mov_b32_e32 v121, v2
	v_mov_b32_e32 v122, v2
	v_mov_b32_e32 v123, v2
	v_mov_b32_e32 v124, v2
	v_mov_b32_e32 v125, v2
	v_mov_b32_e32 v126, v2
	v_mov_b32_e32 v127, v2
	v_mov_b32_e32 v128, v2
	v_mov_b32_e32 v129, v2
